# v072 + non-temporal (nt) hint on GEMM epilogue stores to keep A/B operand tiles resident in L2
# speedup vs baseline: 1.0071x; 1.0071x over previous
.Lgemm_epi0:
	s_mov_b32 s56, 0xbfb8aa3b
	v_lshl_or_b32 v156, s47, 7, v148
	v_ashrrev_i32_e32 v157, 31, v156
	v_lshl_add_u32 v152, s22, 8, v146
	v_lshlrev_b64 v[234:235], 1, v[156:157]
	v_lshl_add_u64 v[234:235], s[4:5], 0, v[234:235]
	s_and_b64 vcc, exec, s[2:3]
	s_mov_b32 s47, s8
	s_mov_b32 s22, s12
	s_mov_b64 s[26:27], s[20:21]
	s_mov_b64 s[24:25], s[14:15]
	v_mad_i64_i32 v[236:237], s[0:1], v152, s46, v[234:235]
	v_pk_mul_f32 v[226:227], v[126:127], s[56:57] op_sel_hi:[1,0]
	v_pk_mul_f32 v[228:229], v[128:129], s[56:57] op_sel_hi:[1,0]
	v_pk_mul_f32 v[230:231], v[122:123], s[56:57] op_sel_hi:[1,0]
	v_pk_mul_f32 v[232:233], v[124:125], s[56:57] op_sel_hi:[1,0]
	v_exp_f32_e32 v226, v226
	v_exp_f32_e32 v227, v227
	v_exp_f32_e32 v228, v228
	v_exp_f32_e32 v229, v229
	v_exp_f32_e32 v230, v230
	v_exp_f32_e32 v231, v231
	v_exp_f32_e32 v232, v232
	v_exp_f32_e32 v233, v233
	v_pk_add_f32 v[226:227], v[226:227], 1.0 op_sel_hi:[1,0]
	v_pk_add_f32 v[228:229], v[228:229], 1.0 op_sel_hi:[1,0]
	v_pk_add_f32 v[230:231], v[230:231], 1.0 op_sel_hi:[1,0]
	v_pk_add_f32 v[232:233], v[232:233], 1.0 op_sel_hi:[1,0]
	v_rcp_f32_e32 v226, v226
	v_rcp_f32_e32 v227, v227
	v_rcp_f32_e32 v228, v228
	v_rcp_f32_e32 v229, v229
	v_rcp_f32_e32 v230, v230
	v_rcp_f32_e32 v231, v231
	v_rcp_f32_e32 v232, v232
	v_rcp_f32_e32 v233, v233
	v_pk_mul_f32 v[126:127], v[126:127], v[226:227]
	v_pk_mul_f32 v[128:129], v[128:129], v[228:229]
	v_pk_mul_f32 v[122:123], v[122:123], v[230:231]
	v_pk_mul_f32 v[124:125], v[124:125], v[232:233]
	v_pk_mul_f32 v[118:119], v[126:127], v[118:119]
	v_pk_mul_f32 v[120:121], v[128:129], v[120:121]
	v_pk_mul_f32 v[114:115], v[122:123], v[114:115]
	v_pk_mul_f32 v[116:117], v[124:125], v[116:117]
	v_cvt_pk_bf16_f32 v118, v118, v119
	v_cvt_pk_bf16_f32 v119, v120, v121
	v_cvt_pk_bf16_f32 v120, v114, v115
	v_cvt_pk_bf16_f32 v121, v116, v117
	global_store_dwordx4 v[236:237], v[118:121], off nt
	v_add_u32_e32 v153, 16, v152
	v_mad_i64_i32 v[238:239], s[0:1], v153, s46, v[234:235]
	v_pk_mul_f32 v[226:227], v[110:111], s[56:57] op_sel_hi:[1,0]
	v_pk_mul_f32 v[228:229], v[112:113], s[56:57] op_sel_hi:[1,0]
	v_pk_mul_f32 v[230:231], v[106:107], s[56:57] op_sel_hi:[1,0]
	v_pk_mul_f32 v[232:233], v[108:109], s[56:57] op_sel_hi:[1,0]
	v_exp_f32_e32 v226, v226
	v_exp_f32_e32 v227, v227
	v_exp_f32_e32 v228, v228
	v_exp_f32_e32 v229, v229
	v_exp_f32_e32 v230, v230
	v_exp_f32_e32 v231, v231
	v_exp_f32_e32 v232, v232
	v_exp_f32_e32 v233, v233
	v_pk_add_f32 v[226:227], v[226:227], 1.0 op_sel_hi:[1,0]
	v_pk_add_f32 v[228:229], v[228:229], 1.0 op_sel_hi:[1,0]
	v_pk_add_f32 v[230:231], v[230:231], 1.0 op_sel_hi:[1,0]
	v_pk_add_f32 v[232:233], v[232:233], 1.0 op_sel_hi:[1,0]
	v_rcp_f32_e32 v226, v226
	v_rcp_f32_e32 v227, v227
	v_rcp_f32_e32 v228, v228
	v_rcp_f32_e32 v229, v229
	v_rcp_f32_e32 v230, v230
	v_rcp_f32_e32 v231, v231
	v_rcp_f32_e32 v232, v232
	v_rcp_f32_e32 v233, v233
	v_pk_mul_f32 v[110:111], v[110:111], v[226:227]
	v_pk_mul_f32 v[112:113], v[112:113], v[228:229]
	v_pk_mul_f32 v[106:107], v[106:107], v[230:231]
	v_pk_mul_f32 v[108:109], v[108:109], v[232:233]
	v_pk_mul_f32 v[102:103], v[110:111], v[102:103]
	v_pk_mul_f32 v[104:105], v[112:113], v[104:105]
	v_pk_mul_f32 v[98:99], v[106:107], v[98:99]
	v_pk_mul_f32 v[100:101], v[108:109], v[100:101]
	v_cvt_pk_bf16_f32 v102, v102, v103
	v_cvt_pk_bf16_f32 v103, v104, v105
	v_cvt_pk_bf16_f32 v104, v98, v99
	v_cvt_pk_bf16_f32 v105, v100, v101
	global_store_dwordx4 v[238:239], v[102:105], off nt
	v_add_u32_e32 v153, 32, v152
	v_mad_i64_i32 v[236:237], s[0:1], v153, s46, v[234:235]
	v_pk_mul_f32 v[226:227], v[94:95], s[56:57] op_sel_hi:[1,0]
	v_pk_mul_f32 v[228:229], v[96:97], s[56:57] op_sel_hi:[1,0]
	v_pk_mul_f32 v[230:231], v[90:91], s[56:57] op_sel_hi:[1,0]
	v_pk_mul_f32 v[232:233], v[92:93], s[56:57] op_sel_hi:[1,0]
	v_exp_f32_e32 v226, v226
	v_exp_f32_e32 v227, v227
	v_exp_f32_e32 v228, v228
	v_exp_f32_e32 v229, v229
	v_exp_f32_e32 v230, v230
	v_exp_f32_e32 v231, v231
	v_exp_f32_e32 v232, v232
	v_exp_f32_e32 v233, v233
	v_pk_add_f32 v[226:227], v[226:227], 1.0 op_sel_hi:[1,0]
	v_pk_add_f32 v[228:229], v[228:229], 1.0 op_sel_hi:[1,0]
	v_pk_add_f32 v[230:231], v[230:231], 1.0 op_sel_hi:[1,0]
	v_pk_add_f32 v[232:233], v[232:233], 1.0 op_sel_hi:[1,0]
	v_rcp_f32_e32 v226, v226
	v_rcp_f32_e32 v227, v227
	v_rcp_f32_e32 v228, v228
	v_rcp_f32_e32 v229, v229
	v_rcp_f32_e32 v230, v230
	v_rcp_f32_e32 v231, v231
	v_rcp_f32_e32 v232, v232
	v_rcp_f32_e32 v233, v233
	v_pk_mul_f32 v[94:95], v[94:95], v[226:227]
	v_pk_mul_f32 v[96:97], v[96:97], v[228:229]
	v_pk_mul_f32 v[90:91], v[90:91], v[230:231]
	v_pk_mul_f32 v[92:93], v[92:93], v[232:233]
	v_pk_mul_f32 v[86:87], v[94:95], v[86:87]
	v_pk_mul_f32 v[88:89], v[96:97], v[88:89]
	v_pk_mul_f32 v[82:83], v[90:91], v[82:83]
	v_pk_mul_f32 v[84:85], v[92:93], v[84:85]
	v_cvt_pk_bf16_f32 v86, v86, v87
	v_cvt_pk_bf16_f32 v87, v88, v89
	v_cvt_pk_bf16_f32 v88, v82, v83
	v_cvt_pk_bf16_f32 v89, v84, v85
	global_store_dwordx4 v[236:237], v[86:89], off nt
	v_add_u32_e32 v153, 48, v152
	v_mad_i64_i32 v[238:239], s[0:1], v153, s46, v[234:235]
	v_pk_mul_f32 v[226:227], v[78:79], s[56:57] op_sel_hi:[1,0]
	v_pk_mul_f32 v[228:229], v[80:81], s[56:57] op_sel_hi:[1,0]
	v_pk_mul_f32 v[230:231], v[74:75], s[56:57] op_sel_hi:[1,0]
	v_pk_mul_f32 v[232:233], v[76:77], s[56:57] op_sel_hi:[1,0]
	v_exp_f32_e32 v226, v226
	v_exp_f32_e32 v227, v227
	v_exp_f32_e32 v228, v228
	v_exp_f32_e32 v229, v229
	v_exp_f32_e32 v230, v230
	v_exp_f32_e32 v231, v231
	v_exp_f32_e32 v232, v232
	v_exp_f32_e32 v233, v233
	v_pk_add_f32 v[226:227], v[226:227], 1.0 op_sel_hi:[1,0]
	v_pk_add_f32 v[228:229], v[228:229], 1.0 op_sel_hi:[1,0]
	v_pk_add_f32 v[230:231], v[230:231], 1.0 op_sel_hi:[1,0]
	v_pk_add_f32 v[232:233], v[232:233], 1.0 op_sel_hi:[1,0]
	v_rcp_f32_e32 v226, v226
	v_rcp_f32_e32 v227, v227
	v_rcp_f32_e32 v228, v228
	v_rcp_f32_e32 v229, v229
	v_rcp_f32_e32 v230, v230
	v_rcp_f32_e32 v231, v231
	v_rcp_f32_e32 v232, v232
	v_rcp_f32_e32 v233, v233
	v_pk_mul_f32 v[78:79], v[78:79], v[226:227]
	v_pk_mul_f32 v[80:81], v[80:81], v[228:229]
	v_pk_mul_f32 v[74:75], v[74:75], v[230:231]
	v_pk_mul_f32 v[76:77], v[76:77], v[232:233]
	v_pk_mul_f32 v[70:71], v[78:79], v[70:71]
	v_pk_mul_f32 v[72:73], v[80:81], v[72:73]
	v_pk_mul_f32 v[66:67], v[74:75], v[66:67]
	v_pk_mul_f32 v[68:69], v[76:77], v[68:69]
	v_cvt_pk_bf16_f32 v70, v70, v71
	v_cvt_pk_bf16_f32 v71, v72, v73
	v_cvt_pk_bf16_f32 v72, v66, v67
	v_cvt_pk_bf16_f32 v73, v68, v69
	global_store_dwordx4 v[238:239], v[70:73], off nt
	v_add_u32_e32 v153, 128, v152
	v_mad_i64_i32 v[236:237], s[0:1], v153, s46, v[234:235]
	v_pk_mul_f32 v[226:227], v[62:63], s[56:57] op_sel_hi:[1,0]
	v_pk_mul_f32 v[228:229], v[64:65], s[56:57] op_sel_hi:[1,0]
	v_pk_mul_f32 v[230:231], v[58:59], s[56:57] op_sel_hi:[1,0]
	v_pk_mul_f32 v[232:233], v[60:61], s[56:57] op_sel_hi:[1,0]
	v_exp_f32_e32 v226, v226
	v_exp_f32_e32 v227, v227
	v_exp_f32_e32 v228, v228
	v_exp_f32_e32 v229, v229
	v_exp_f32_e32 v230, v230
	v_exp_f32_e32 v231, v231
	v_exp_f32_e32 v232, v232
	v_exp_f32_e32 v233, v233
	v_pk_add_f32 v[226:227], v[226:227], 1.0 op_sel_hi:[1,0]
	v_pk_add_f32 v[228:229], v[228:229], 1.0 op_sel_hi:[1,0]
	v_pk_add_f32 v[230:231], v[230:231], 1.0 op_sel_hi:[1,0]
	v_pk_add_f32 v[232:233], v[232:233], 1.0 op_sel_hi:[1,0]
	v_rcp_f32_e32 v226, v226
	v_rcp_f32_e32 v227, v227
	v_rcp_f32_e32 v228, v228
	v_rcp_f32_e32 v229, v229
	v_rcp_f32_e32 v230, v230
	v_rcp_f32_e32 v231, v231
	v_rcp_f32_e32 v232, v232
	v_rcp_f32_e32 v233, v233
	v_pk_mul_f32 v[62:63], v[62:63], v[226:227]
	v_pk_mul_f32 v[64:65], v[64:65], v[228:229]
	v_pk_mul_f32 v[58:59], v[58:59], v[230:231]
	v_pk_mul_f32 v[60:61], v[60:61], v[232:233]
	v_pk_mul_f32 v[54:55], v[62:63], v[54:55]
	v_pk_mul_f32 v[56:57], v[64:65], v[56:57]
	v_pk_mul_f32 v[50:51], v[58:59], v[50:51]
	v_pk_mul_f32 v[52:53], v[60:61], v[52:53]
	v_cvt_pk_bf16_f32 v54, v54, v55
	v_cvt_pk_bf16_f32 v55, v56, v57
	v_cvt_pk_bf16_f32 v56, v50, v51
	v_cvt_pk_bf16_f32 v57, v52, v53
	global_store_dwordx4 v[236:237], v[54:57], off nt
	v_add_u32_e32 v153, 144, v152
	v_mad_i64_i32 v[238:239], s[0:1], v153, s46, v[234:235]
	v_pk_mul_f32 v[226:227], v[46:47], s[56:57] op_sel_hi:[1,0]
	v_pk_mul_f32 v[228:229], v[48:49], s[56:57] op_sel_hi:[1,0]
	v_pk_mul_f32 v[230:231], v[42:43], s[56:57] op_sel_hi:[1,0]
	v_pk_mul_f32 v[232:233], v[44:45], s[56:57] op_sel_hi:[1,0]
	v_exp_f32_e32 v226, v226
	v_exp_f32_e32 v227, v227
	v_exp_f32_e32 v228, v228
	v_exp_f32_e32 v229, v229
	v_exp_f32_e32 v230, v230
	v_exp_f32_e32 v231, v231
	v_exp_f32_e32 v232, v232
	v_exp_f32_e32 v233, v233
	v_pk_add_f32 v[226:227], v[226:227], 1.0 op_sel_hi:[1,0]
	v_pk_add_f32 v[228:229], v[228:229], 1.0 op_sel_hi:[1,0]
	v_pk_add_f32 v[230:231], v[230:231], 1.0 op_sel_hi:[1,0]
	v_pk_add_f32 v[232:233], v[232:233], 1.0 op_sel_hi:[1,0]
	v_rcp_f32_e32 v226, v226
	v_rcp_f32_e32 v227, v227
	v_rcp_f32_e32 v228, v228
	v_rcp_f32_e32 v229, v229
	v_rcp_f32_e32 v230, v230
	v_rcp_f32_e32 v231, v231
	v_rcp_f32_e32 v232, v232
	v_rcp_f32_e32 v233, v233
	v_pk_mul_f32 v[46:47], v[46:47], v[226:227]
	v_pk_mul_f32 v[48:49], v[48:49], v[228:229]
	v_pk_mul_f32 v[42:43], v[42:43], v[230:231]
	v_pk_mul_f32 v[44:45], v[44:45], v[232:233]
	v_pk_mul_f32 v[38:39], v[46:47], v[38:39]
	v_pk_mul_f32 v[40:41], v[48:49], v[40:41]
	v_pk_mul_f32 v[34:35], v[42:43], v[34:35]
	v_pk_mul_f32 v[36:37], v[44:45], v[36:37]
	v_cvt_pk_bf16_f32 v38, v38, v39
	v_cvt_pk_bf16_f32 v39, v40, v41
	v_cvt_pk_bf16_f32 v40, v34, v35
	v_cvt_pk_bf16_f32 v41, v36, v37
	global_store_dwordx4 v[238:239], v[38:41], off nt
	v_add_u32_e32 v153, 160, v152
	v_mad_i64_i32 v[236:237], s[0:1], v153, s46, v[234:235]
	v_pk_mul_f32 v[226:227], v[30:31], s[56:57] op_sel_hi:[1,0]
	v_pk_mul_f32 v[228:229], v[32:33], s[56:57] op_sel_hi:[1,0]
	v_pk_mul_f32 v[230:231], v[26:27], s[56:57] op_sel_hi:[1,0]
	v_pk_mul_f32 v[232:233], v[28:29], s[56:57] op_sel_hi:[1,0]
	v_exp_f32_e32 v226, v226
	v_exp_f32_e32 v227, v227
	v_exp_f32_e32 v228, v228
	v_exp_f32_e32 v229, v229
	v_exp_f32_e32 v230, v230
	v_exp_f32_e32 v231, v231
	v_exp_f32_e32 v232, v232
	v_exp_f32_e32 v233, v233
	v_pk_add_f32 v[226:227], v[226:227], 1.0 op_sel_hi:[1,0]
	v_pk_add_f32 v[228:229], v[228:229], 1.0 op_sel_hi:[1,0]
	v_pk_add_f32 v[230:231], v[230:231], 1.0 op_sel_hi:[1,0]
	v_pk_add_f32 v[232:233], v[232:233], 1.0 op_sel_hi:[1,0]
	v_rcp_f32_e32 v226, v226
	v_rcp_f32_e32 v227, v227
	v_rcp_f32_e32 v228, v228
	v_rcp_f32_e32 v229, v229
	v_rcp_f32_e32 v230, v230
	v_rcp_f32_e32 v231, v231
	v_rcp_f32_e32 v232, v232
	v_rcp_f32_e32 v233, v233
	v_pk_mul_f32 v[30:31], v[30:31], v[226:227]
	v_pk_mul_f32 v[32:33], v[32:33], v[228:229]
	v_pk_mul_f32 v[26:27], v[26:27], v[230:231]
	v_pk_mul_f32 v[28:29], v[28:29], v[232:233]
	v_pk_mul_f32 v[22:23], v[30:31], v[22:23]
	v_pk_mul_f32 v[24:25], v[32:33], v[24:25]
	v_pk_mul_f32 v[18:19], v[26:27], v[18:19]
	v_pk_mul_f32 v[20:21], v[28:29], v[20:21]
	v_cvt_pk_bf16_f32 v22, v22, v23
	v_cvt_pk_bf16_f32 v23, v24, v25
	v_cvt_pk_bf16_f32 v24, v18, v19
	v_cvt_pk_bf16_f32 v25, v20, v21
	global_store_dwordx4 v[236:237], v[22:25], off nt
	v_add_u32_e32 v153, 176, v152
	v_mad_i64_i32 v[238:239], s[0:1], v153, s46, v[234:235]
	v_pk_mul_f32 v[226:227], v[14:15], s[56:57] op_sel_hi:[1,0]
	v_pk_mul_f32 v[228:229], v[16:17], s[56:57] op_sel_hi:[1,0]
	v_pk_mul_f32 v[230:231], v[10:11], s[56:57] op_sel_hi:[1,0]
	v_pk_mul_f32 v[232:233], v[12:13], s[56:57] op_sel_hi:[1,0]
	v_exp_f32_e32 v226, v226
	v_exp_f32_e32 v227, v227
	v_exp_f32_e32 v228, v228
	v_exp_f32_e32 v229, v229
	v_exp_f32_e32 v230, v230
	v_exp_f32_e32 v231, v231
	v_exp_f32_e32 v232, v232
	v_exp_f32_e32 v233, v233
	v_pk_add_f32 v[226:227], v[226:227], 1.0 op_sel_hi:[1,0]
	v_pk_add_f32 v[228:229], v[228:229], 1.0 op_sel_hi:[1,0]
	v_pk_add_f32 v[230:231], v[230:231], 1.0 op_sel_hi:[1,0]
	v_pk_add_f32 v[232:233], v[232:233], 1.0 op_sel_hi:[1,0]
	v_rcp_f32_e32 v226, v226
	v_rcp_f32_e32 v227, v227
	v_rcp_f32_e32 v228, v228
	v_rcp_f32_e32 v229, v229
	v_rcp_f32_e32 v230, v230
	v_rcp_f32_e32 v231, v231
	v_rcp_f32_e32 v232, v232
	v_rcp_f32_e32 v233, v233
	v_pk_mul_f32 v[14:15], v[14:15], v[226:227]
	v_pk_mul_f32 v[16:17], v[16:17], v[228:229]
	v_pk_mul_f32 v[10:11], v[10:11], v[230:231]
	v_pk_mul_f32 v[12:13], v[12:13], v[232:233]
	v_pk_mul_f32 v[6:7], v[14:15], v[6:7]
	v_pk_mul_f32 v[8:9], v[16:17], v[8:9]
	v_pk_mul_f32 v[2:3], v[10:11], v[2:3]
	v_pk_mul_f32 v[4:5], v[12:13], v[4:5]
	v_cvt_pk_bf16_f32 v6, v6, v7
	v_cvt_pk_bf16_f32 v7, v8, v9
	v_cvt_pk_bf16_f32 v8, v2, v3
	v_cvt_pk_bf16_f32 v9, v4, v5
	global_store_dwordx4 v[238:239], v[6:9], off nt
	s_cbranch_vccz .LBB0_72
	s_waitcnt vmcnt(0)
	s_cmpk_gt_u32 s30, 0xff
	s_cbranch_scc1 .LBB0_79
	s_barrier

.Lgemm_epi1:
	v_lshl_add_u32 v198, s49, 8, v206
	v_lshl_or_b32 v194, s48, 8, v208
	v_ashrrev_i32_e32 v195, 31, v194
	v_ashrrev_i32_e32 v199, 31, v198
	v_lshl_add_u64 v[196:197], v[194:195], 2, s[12:13]
	v_lshlrev_b64 v[130:131], 12, v[198:199]
	v_lshl_add_u64 v[130:131], v[196:197], 0, v[130:131]
	global_load_dwordx4 v[214:217], v[130:131], off
	global_load_dwordx4 v[218:221], v[130:131], off offset:16
	global_load_dwordx4 v[222:225], v[130:131], off offset:512
	global_load_dwordx4 v[226:229], v[130:131], off offset:528
	v_or_b32_e32 v204, 16, v198
	v_or_b32_e32 v202, 32, v198
	v_or_b32_e32 v200, 48, v198
	v_ashrrev_i32_e32 v205, 31, v204
	v_ashrrev_i32_e32 v203, 31, v202
	v_ashrrev_i32_e32 v201, 31, v200
	v_lshlrev_b64 v[130:131], 12, v[204:205]
	v_lshlrev_b64 v[132:133], 12, v[202:203]
	v_lshlrev_b64 v[134:135], 12, v[200:201]
	v_lshl_add_u64 v[130:131], v[196:197], 0, v[130:131]
	v_lshl_add_u64 v[132:133], v[196:197], 0, v[132:133]
	v_lshl_add_u64 v[134:135], v[196:197], 0, v[134:135]
	global_load_dwordx4 v[170:173], v[130:131], off offset:16
	global_load_dwordx4 v[174:177], v[130:131], off
	global_load_dwordx4 v[162:165], v[130:131], off offset:528
	global_load_dwordx4 v[166:169], v[130:131], off offset:512
	global_load_dwordx4 v[154:157], v[132:133], off offset:16
	global_load_dwordx4 v[158:161], v[132:133], off
	global_load_dwordx4 v[146:149], v[132:133], off offset:528
	global_load_dwordx4 v[150:153], v[132:133], off offset:512
	global_load_dwordx4 v[138:141], v[134:135], off offset:16
	global_load_dwordx4 v[142:145], v[134:135], off
	s_nop 0
	global_load_dwordx4 v[130:133], v[134:135], off offset:528
	s_nop 0
	global_load_dwordx4 v[134:137], v[134:135], off offset:512
	v_and_b32_e32 v230, 64, v212
	v_xor_b32_e32 v213, 16, v212
	v_add_u32_e32 v233, 64, v230
	v_cmp_lt_i32_e32 vcc, v213, v233
	v_xor_b32_e32 v232, 32, v212
	v_lshlrev_b64 v[230:231], 11, v[198:199]
	v_cndmask_b32_e32 v213, v212, v213, vcc
	v_lshlrev_b32_e32 v213, 2, v213
	v_cmp_lt_i32_e32 vcc, v232, v233
	v_lshl_add_u64 v[230:231], s[68:69], 0, v[230:231]
	v_lshl_add_u64 v[230:231], v[194:195], 1, v[230:231]
	v_cndmask_b32_e32 v232, v212, v232, vcc
	s_waitcnt vmcnt(0)
	v_pk_fma_f32 v[126:127], v[126:127], 0.5, v[214:215] op_sel_hi:[1,0,1]
	v_pk_fma_f32 v[128:129], v[128:129], 0.5, v[216:217] op_sel_hi:[1,0,1]
	v_pk_fma_f32 v[118:119], v[118:119], 0.5, v[222:223] op_sel_hi:[1,0,1]
	v_pk_fma_f32 v[214:215], v[116:117], 0.5, v[228:229] op_sel_hi:[1,0,1]
	v_mul_f32_e32 v116, v127, v127
	v_mul_f32_e32 v117, v119, v119
	v_pk_fma_f32 v[120:121], v[120:121], 0.5, v[224:225] op_sel_hi:[1,0,1]
	v_fmac_f32_e32 v116, v126, v126
	v_fmac_f32_e32 v117, v118, v118
	v_fmac_f32_e32 v116, v128, v128
	v_fmac_f32_e32 v117, v120, v120
	v_pk_fma_f32 v[122:123], v[122:123], 0.5, v[218:219] op_sel_hi:[1,0,1]
	v_pk_fma_f32 v[216:217], v[114:115], 0.5, v[226:227] op_sel_hi:[1,0,1]
	v_fmac_f32_e32 v116, v129, v129
	v_fmac_f32_e32 v117, v121, v121
	v_fmac_f32_e32 v116, v122, v122
	v_fmac_f32_e32 v117, v216, v216
	v_pk_fma_f32 v[124:125], v[124:125], 0.5, v[220:221] op_sel_hi:[1,0,1]
	v_fmac_f32_e32 v116, v123, v123
	v_fmac_f32_e32 v117, v217, v217
	v_fmac_f32_e32 v116, v124, v124
	v_fmac_f32_e32 v117, v214, v214
	v_fmac_f32_e32 v116, v125, v125
	v_fmac_f32_e32 v117, v215, v215
	v_cvt_pk_bf16_f32 v114, v126, v127
	v_add_f32_e32 v126, v116, v117
	ds_bpermute_b32 v127, v213, v126
	v_cvt_pk_bf16_f32 v115, v128, v129
	v_cvt_pk_bf16_f32 v116, v122, v123
	v_cvt_pk_bf16_f32 v117, v124, v125
	global_store_dwordx4 v[230:231], v[114:117], off nt
	v_lshlrev_b32_e32 v122, 2, v232
	v_cvt_pk_bf16_f32 v118, v118, v119
	s_waitcnt lgkmcnt(0)
	v_add_f32_e32 v114, v126, v127
	ds_bpermute_b32 v115, v122, v114
	v_cvt_pk_bf16_f32 v119, v120, v121
	v_cvt_pk_bf16_f32 v120, v216, v217
	v_cvt_pk_bf16_f32 v121, v214, v215
	global_store_dwordx4 v[230:231], v[118:121], off offset:256 nt
	s_and_saveexec_b64 s[22:23], s[2:3]
	s_cbranch_execz .LBB0_122
	s_waitcnt lgkmcnt(0)
	v_add_f32_e32 v116, v114, v115
	v_lshl_add_u64 v[114:115], v[198:199], 2, s[14:15]
	global_atomic_add_f32 v[114:115], v116, off
.LBB0_122:
	s_or_b64 exec, exec, s[22:23]
	v_pk_fma_f32 v[110:111], v[110:111], 0.5, v[174:175] op_sel_hi:[1,0,1]
	v_pk_fma_f32 v[102:103], v[102:103], 0.5, v[166:167] op_sel_hi:[1,0,1]
	v_pk_fma_f32 v[124:125], v[98:99], 0.5, v[162:163] op_sel_hi:[1,0,1]
	v_mul_f32_e32 v98, v111, v111
	v_mul_f32_e32 v99, v103, v103
	v_pk_fma_f32 v[112:113], v[112:113], 0.5, v[176:177] op_sel_hi:[1,0,1]
	v_pk_fma_f32 v[104:105], v[104:105], 0.5, v[168:169] op_sel_hi:[1,0,1]
	v_fmac_f32_e32 v98, v110, v110
	v_fmac_f32_e32 v99, v102, v102
	v_fmac_f32_e32 v98, v112, v112
	v_fmac_f32_e32 v99, v104, v104
	v_pk_fma_f32 v[118:119], v[106:107], 0.5, v[170:171] op_sel_hi:[1,0,1]
	v_fmac_f32_e32 v98, v113, v113
	v_fmac_f32_e32 v99, v105, v105
	v_fmac_f32_e32 v98, v118, v118
	v_fmac_f32_e32 v99, v124, v124
	v_pk_fma_f32 v[116:117], v[108:109], 0.5, v[172:173] op_sel_hi:[1,0,1]
	v_pk_fma_f32 v[120:121], v[100:101], 0.5, v[164:165] op_sel_hi:[1,0,1]
	v_fmac_f32_e32 v98, v119, v119
	v_fmac_f32_e32 v99, v125, v125
	v_fmac_f32_e32 v98, v116, v116
	v_fmac_f32_e32 v99, v120, v120
	v_fmac_f32_e32 v98, v117, v117
	v_fmac_f32_e32 v99, v121, v121
	v_add_f32_e32 v101, v98, v99
	v_cvt_pk_bf16_f32 v107, v112, v113
	ds_bpermute_b32 v112, v213, v101
	s_waitcnt lgkmcnt(1)
	v_lshlrev_b64 v[114:115], 11, v[204:205]
	v_lshl_add_u64 v[98:99], s[68:69], 0, v[114:115]
	v_cvt_pk_bf16_f32 v106, v110, v111
	v_lshl_add_u64 v[110:111], v[194:195], 1, v[98:99]
	s_waitcnt lgkmcnt(0)
	v_add_f32_e32 v98, v101, v112
	ds_bpermute_b32 v99, v122, v98
	v_cvt_pk_bf16_f32 v108, v118, v119
	v_cvt_pk_bf16_f32 v109, v116, v117
	v_cvt_pk_bf16_f32 v100, v102, v103
	v_cvt_pk_bf16_f32 v101, v104, v105
	v_cvt_pk_bf16_f32 v102, v124, v125
	v_cvt_pk_bf16_f32 v103, v120, v121
	global_store_dwordx4 v[110:111], v[106:109], off nt
	global_store_dwordx4 v[110:111], v[100:103], off offset:256 nt
	s_and_saveexec_b64 s[22:23], s[2:3]
	s_cbranch_execz .LBB0_124
	s_waitcnt lgkmcnt(0)
	v_add_f32_e32 v100, v98, v99
	v_lshl_add_u64 v[98:99], v[204:205], 2, s[14:15]
	global_atomic_add_f32 v[98:99], v100, off
.LBB0_124:
	s_or_b64 exec, exec, s[22:23]
	v_pk_fma_f32 v[94:95], v[94:95], 0.5, v[158:159] op_sel_hi:[1,0,1]
	v_pk_fma_f32 v[86:87], v[86:87], 0.5, v[150:151] op_sel_hi:[1,0,1]
	v_pk_fma_f32 v[106:107], v[82:83], 0.5, v[146:147] op_sel_hi:[1,0,1]
	v_mul_f32_e32 v82, v95, v95
	v_mul_f32_e32 v83, v87, v87
	v_pk_fma_f32 v[96:97], v[96:97], 0.5, v[160:161] op_sel_hi:[1,0,1]
	v_pk_fma_f32 v[88:89], v[88:89], 0.5, v[152:153] op_sel_hi:[1,0,1]
	v_fmac_f32_e32 v82, v94, v94
	v_fmac_f32_e32 v83, v86, v86
	v_fmac_f32_e32 v82, v96, v96
	v_fmac_f32_e32 v83, v88, v88
	v_pk_fma_f32 v[102:103], v[90:91], 0.5, v[154:155] op_sel_hi:[1,0,1]
	v_fmac_f32_e32 v82, v97, v97
	v_fmac_f32_e32 v83, v89, v89
	v_fmac_f32_e32 v82, v102, v102
	v_fmac_f32_e32 v83, v106, v106
	v_pk_fma_f32 v[100:101], v[92:93], 0.5, v[156:157] op_sel_hi:[1,0,1]
	v_pk_fma_f32 v[104:105], v[84:85], 0.5, v[148:149] op_sel_hi:[1,0,1]
	v_fmac_f32_e32 v82, v103, v103
	v_fmac_f32_e32 v83, v107, v107
	v_fmac_f32_e32 v82, v100, v100
	v_fmac_f32_e32 v83, v104, v104
	v_fmac_f32_e32 v82, v101, v101
	v_fmac_f32_e32 v83, v105, v105
	v_add_f32_e32 v85, v82, v83
	v_cvt_pk_bf16_f32 v91, v96, v97
	ds_bpermute_b32 v96, v213, v85
	s_waitcnt lgkmcnt(1)
	v_lshlrev_b64 v[98:99], 11, v[202:203]
	v_lshl_add_u64 v[82:83], s[68:69], 0, v[98:99]
	v_cvt_pk_bf16_f32 v90, v94, v95
	v_lshl_add_u64 v[94:95], v[194:195], 1, v[82:83]
	s_waitcnt lgkmcnt(0)
	v_add_f32_e32 v82, v85, v96
	ds_bpermute_b32 v83, v122, v82
	v_cvt_pk_bf16_f32 v92, v102, v103
	v_cvt_pk_bf16_f32 v93, v100, v101
	v_cvt_pk_bf16_f32 v84, v86, v87
	v_cvt_pk_bf16_f32 v85, v88, v89
	v_cvt_pk_bf16_f32 v86, v106, v107
	v_cvt_pk_bf16_f32 v87, v104, v105
	global_store_dwordx4 v[94:95], v[90:93], off nt
	global_store_dwordx4 v[94:95], v[84:87], off offset:256 nt
	s_and_saveexec_b64 s[22:23], s[2:3]
	s_cbranch_execz .LBB0_126
	s_waitcnt lgkmcnt(0)
	v_add_f32_e32 v84, v82, v83
	v_lshl_add_u64 v[82:83], v[202:203], 2, s[14:15]
	global_atomic_add_f32 v[82:83], v84, off
.LBB0_126:
	s_or_b64 exec, exec, s[22:23]
	v_pk_fma_f32 v[78:79], v[78:79], 0.5, v[142:143] op_sel_hi:[1,0,1]
	v_pk_fma_f32 v[70:71], v[70:71], 0.5, v[134:135] op_sel_hi:[1,0,1]
	v_pk_fma_f32 v[90:91], v[66:67], 0.5, v[130:131] op_sel_hi:[1,0,1]
	v_mul_f32_e32 v66, v79, v79
	v_mul_f32_e32 v67, v71, v71
	v_pk_fma_f32 v[80:81], v[80:81], 0.5, v[144:145] op_sel_hi:[1,0,1]
	v_pk_fma_f32 v[72:73], v[72:73], 0.5, v[136:137] op_sel_hi:[1,0,1]
	v_fmac_f32_e32 v66, v78, v78
	v_fmac_f32_e32 v67, v70, v70
	v_fmac_f32_e32 v66, v80, v80
	v_fmac_f32_e32 v67, v72, v72
	v_pk_fma_f32 v[86:87], v[74:75], 0.5, v[138:139] op_sel_hi:[1,0,1]
	v_fmac_f32_e32 v66, v81, v81
	v_fmac_f32_e32 v67, v73, v73
	v_fmac_f32_e32 v66, v86, v86
	v_fmac_f32_e32 v67, v90, v90
	v_pk_fma_f32 v[84:85], v[76:77], 0.5, v[140:141] op_sel_hi:[1,0,1]
	v_pk_fma_f32 v[88:89], v[68:69], 0.5, v[132:133] op_sel_hi:[1,0,1]
	v_fmac_f32_e32 v66, v87, v87
	v_fmac_f32_e32 v67, v91, v91
	v_fmac_f32_e32 v66, v84, v84
	v_fmac_f32_e32 v67, v88, v88
	v_fmac_f32_e32 v66, v85, v85
	v_fmac_f32_e32 v67, v89, v89
	v_add_f32_e32 v69, v66, v67
	v_cvt_pk_bf16_f32 v75, v80, v81
	ds_bpermute_b32 v80, v213, v69
	s_waitcnt lgkmcnt(1)
	v_lshlrev_b64 v[82:83], 11, v[200:201]
	v_lshl_add_u64 v[66:67], s[68:69], 0, v[82:83]
	v_cvt_pk_bf16_f32 v74, v78, v79
	v_lshl_add_u64 v[78:79], v[194:195], 1, v[66:67]
	s_waitcnt lgkmcnt(0)
	v_add_f32_e32 v66, v69, v80
	ds_bpermute_b32 v67, v122, v66
	v_cvt_pk_bf16_f32 v76, v86, v87
	v_cvt_pk_bf16_f32 v77, v84, v85
	v_cvt_pk_bf16_f32 v68, v70, v71
	v_cvt_pk_bf16_f32 v69, v72, v73
	v_cvt_pk_bf16_f32 v70, v90, v91
	v_cvt_pk_bf16_f32 v71, v88, v89
	global_store_dwordx4 v[78:79], v[74:77], off nt
	global_store_dwordx4 v[78:79], v[68:71], off offset:256 nt
	s_and_saveexec_b64 s[22:23], s[2:3]
	s_cbranch_execz .LBB0_128
	s_waitcnt lgkmcnt(0)
	v_add_f32_e32 v68, v66, v67
	v_lshl_add_u64 v[66:67], v[200:201], 2, s[14:15]
	global_atomic_add_f32 v[66:67], v68, off
.LBB0_128:
	s_or_b64 exec, exec, s[22:23]
	v_add_u32_e32 v120, 0x80, v198
	v_ashrrev_i32_e32 v121, 31, v120
	s_waitcnt lgkmcnt(0)
	v_lshlrev_b64 v[66:67], 12, v[120:121]
	v_lshl_add_u64 v[66:67], v[196:197], 0, v[66:67]
	global_load_dwordx4 v[124:127], v[66:67], off
	global_load_dwordx4 v[128:131], v[66:67], off offset:16
	global_load_dwordx4 v[132:135], v[66:67], off offset:512
	global_load_dwordx4 v[136:139], v[66:67], off offset:528
	v_add_u32_e32 v118, 0x90, v198
	v_add_u32_e32 v116, 0xa0, v198
	v_add_u32_e32 v114, 0xb0, v198
	v_ashrrev_i32_e32 v119, 31, v118
	v_ashrrev_i32_e32 v117, 31, v116
	v_ashrrev_i32_e32 v115, 31, v114
	v_lshlrev_b64 v[66:67], 12, v[118:119]
	v_lshlrev_b64 v[68:69], 12, v[116:117]
	v_lshlrev_b64 v[70:71], 12, v[114:115]
	v_lshl_add_u64 v[66:67], v[196:197], 0, v[66:67]
	v_lshl_add_u64 v[68:69], v[196:197], 0, v[68:69]
	v_lshl_add_u64 v[70:71], v[196:197], 0, v[70:71]
	global_load_dwordx4 v[106:109], v[66:67], off offset:16
	global_load_dwordx4 v[110:113], v[66:67], off
	global_load_dwordx4 v[98:101], v[66:67], off offset:528
	global_load_dwordx4 v[102:105], v[66:67], off offset:512
	global_load_dwordx4 v[90:93], v[68:69], off offset:16
	global_load_dwordx4 v[94:97], v[68:69], off
	global_load_dwordx4 v[82:85], v[68:69], off offset:528
	global_load_dwordx4 v[86:89], v[68:69], off offset:512
	global_load_dwordx4 v[74:77], v[70:71], off offset:16
	global_load_dwordx4 v[78:81], v[70:71], off
	s_nop 0
	global_load_dwordx4 v[66:69], v[70:71], off offset:528
	s_nop 0
	global_load_dwordx4 v[70:73], v[70:71], off offset:512
	v_lshlrev_b64 v[140:141], 11, v[120:121]
	s_waitcnt vmcnt(15)
	v_pk_fma_f32 v[62:63], v[62:63], 0.5, v[124:125] op_sel_hi:[1,0,1]
	v_pk_fma_f32 v[64:65], v[64:65], 0.5, v[126:127] op_sel_hi:[1,0,1]
	s_waitcnt vmcnt(13)
	v_pk_fma_f32 v[54:55], v[54:55], 0.5, v[132:133] op_sel_hi:[1,0,1]
	s_waitcnt vmcnt(12)
	v_pk_fma_f32 v[126:127], v[50:51], 0.5, v[136:137] op_sel_hi:[1,0,1]
	v_cvt_pk_bf16_f32 v50, v62, v63
	v_mul_f32_e32 v63, v63, v63
	v_mul_f32_e32 v123, v55, v55
	v_pk_fma_f32 v[56:57], v[56:57], 0.5, v[134:135] op_sel_hi:[1,0,1]
	v_fmac_f32_e32 v63, v62, v62
	v_fmac_f32_e32 v123, v54, v54
	v_fmac_f32_e32 v63, v64, v64
	v_fmac_f32_e32 v123, v56, v56
	v_pk_fma_f32 v[58:59], v[58:59], 0.5, v[128:129] op_sel_hi:[1,0,1]
	v_fmac_f32_e32 v63, v65, v65
	v_fmac_f32_e32 v123, v57, v57
	v_fmac_f32_e32 v63, v58, v58
	v_fmac_f32_e32 v123, v126, v126
	v_pk_fma_f32 v[60:61], v[60:61], 0.5, v[130:131] op_sel_hi:[1,0,1]
	v_pk_fma_f32 v[124:125], v[52:53], 0.5, v[138:139] op_sel_hi:[1,0,1]
	v_fmac_f32_e32 v63, v59, v59
	v_fmac_f32_e32 v123, v127, v127
	v_fmac_f32_e32 v63, v60, v60
	v_fmac_f32_e32 v123, v124, v124
	v_fmac_f32_e32 v63, v61, v61
	v_fmac_f32_e32 v123, v125, v125
	v_cvt_pk_bf16_f32 v53, v60, v61
	v_add_f32_e32 v60, v63, v123
	ds_bpermute_b32 v61, v213, v60
	v_cvt_pk_bf16_f32 v52, v58, v59
	v_lshl_add_u64 v[58:59], s[68:69], 0, v[140:141]
	v_cvt_pk_bf16_f32 v51, v64, v65
	v_lshl_add_u64 v[58:59], v[194:195], 1, v[58:59]
	global_store_dwordx4 v[58:59], v[50:53], off nt
	s_waitcnt lgkmcnt(0)
	s_nop 0
	v_add_f32_e32 v50, v60, v61
	ds_bpermute_b32 v51, v122, v50
	v_cvt_pk_bf16_f32 v52, v54, v55
	v_cvt_pk_bf16_f32 v53, v56, v57
	v_cvt_pk_bf16_f32 v54, v126, v127
	v_cvt_pk_bf16_f32 v55, v124, v125
	global_store_dwordx4 v[58:59], v[52:55], off offset:256 nt
	s_and_saveexec_b64 s[22:23], s[2:3]
	s_cbranch_execz .LBB0_130
	s_waitcnt lgkmcnt(0)
	v_add_f32_e32 v52, v50, v51
	v_lshl_add_u64 v[50:51], v[120:121], 2, s[14:15]
	global_atomic_add_f32 v[50:51], v52, off
.LBB0_130:
	s_or_b64 exec, exec, s[22:23]
	s_waitcnt vmcnt(12)
	v_pk_fma_f32 v[46:47], v[46:47], 0.5, v[110:111] op_sel_hi:[1,0,1]
	s_waitcnt vmcnt(10)
	v_pk_fma_f32 v[38:39], v[38:39], 0.5, v[102:103] op_sel_hi:[1,0,1]
	v_pk_fma_f32 v[58:59], v[34:35], 0.5, v[98:99] op_sel_hi:[1,0,1]
	v_mul_f32_e32 v34, v47, v47
	v_mul_f32_e32 v35, v39, v39
	v_pk_fma_f32 v[48:49], v[48:49], 0.5, v[112:113] op_sel_hi:[1,0,1]
	v_pk_fma_f32 v[40:41], v[40:41], 0.5, v[104:105] op_sel_hi:[1,0,1]
	v_fmac_f32_e32 v34, v46, v46
	v_fmac_f32_e32 v35, v38, v38
	v_fmac_f32_e32 v34, v48, v48
	v_fmac_f32_e32 v35, v40, v40
	v_pk_fma_f32 v[54:55], v[42:43], 0.5, v[106:107] op_sel_hi:[1,0,1]
	v_fmac_f32_e32 v34, v49, v49
	v_fmac_f32_e32 v35, v41, v41
	v_fmac_f32_e32 v34, v54, v54
	v_fmac_f32_e32 v35, v58, v58
	v_pk_fma_f32 v[52:53], v[44:45], 0.5, v[108:109] op_sel_hi:[1,0,1]
	v_pk_fma_f32 v[56:57], v[36:37], 0.5, v[100:101] op_sel_hi:[1,0,1]
	v_fmac_f32_e32 v34, v55, v55
	v_fmac_f32_e32 v35, v59, v59
	v_fmac_f32_e32 v34, v52, v52
	v_fmac_f32_e32 v35, v56, v56
	v_fmac_f32_e32 v34, v53, v53
	v_fmac_f32_e32 v35, v57, v57
	v_add_f32_e32 v37, v34, v35
	v_cvt_pk_bf16_f32 v43, v48, v49
	ds_bpermute_b32 v48, v213, v37
	s_waitcnt lgkmcnt(1)
	v_lshlrev_b64 v[50:51], 11, v[118:119]
	v_lshl_add_u64 v[34:35], s[68:69], 0, v[50:51]
	v_cvt_pk_bf16_f32 v42, v46, v47
	v_lshl_add_u64 v[46:47], v[194:195], 1, v[34:35]
	s_waitcnt lgkmcnt(0)
	v_add_f32_e32 v34, v37, v48
	ds_bpermute_b32 v35, v122, v34
	v_cvt_pk_bf16_f32 v44, v54, v55
	v_cvt_pk_bf16_f32 v45, v52, v53
	v_cvt_pk_bf16_f32 v36, v38, v39
	v_cvt_pk_bf16_f32 v37, v40, v41
	v_cvt_pk_bf16_f32 v38, v58, v59
	v_cvt_pk_bf16_f32 v39, v56, v57
	global_store_dwordx4 v[46:47], v[42:45], off nt
	global_store_dwordx4 v[46:47], v[36:39], off offset:256 nt
	s_and_saveexec_b64 s[22:23], s[2:3]
	s_cbranch_execz .LBB0_132
	s_waitcnt lgkmcnt(0)
	v_add_f32_e32 v36, v34, v35
	v_lshl_add_u64 v[34:35], v[118:119], 2, s[14:15]
	global_atomic_add_f32 v[34:35], v36, off
.LBB0_132:
	s_or_b64 exec, exec, s[22:23]
	s_waitcnt vmcnt(10)
	v_pk_fma_f32 v[30:31], v[30:31], 0.5, v[94:95] op_sel_hi:[1,0,1]
	s_waitcnt vmcnt(8)
	v_pk_fma_f32 v[22:23], v[22:23], 0.5, v[86:87] op_sel_hi:[1,0,1]
	v_pk_fma_f32 v[42:43], v[18:19], 0.5, v[82:83] op_sel_hi:[1,0,1]
	v_mul_f32_e32 v18, v31, v31
	v_mul_f32_e32 v19, v23, v23
	v_pk_fma_f32 v[32:33], v[32:33], 0.5, v[96:97] op_sel_hi:[1,0,1]
	v_pk_fma_f32 v[24:25], v[24:25], 0.5, v[88:89] op_sel_hi:[1,0,1]
	v_fmac_f32_e32 v18, v30, v30
	v_fmac_f32_e32 v19, v22, v22
	v_fmac_f32_e32 v18, v32, v32
	v_fmac_f32_e32 v19, v24, v24
	v_pk_fma_f32 v[38:39], v[26:27], 0.5, v[90:91] op_sel_hi:[1,0,1]
	v_fmac_f32_e32 v18, v33, v33
	v_fmac_f32_e32 v19, v25, v25
	v_fmac_f32_e32 v18, v38, v38
	v_fmac_f32_e32 v19, v42, v42
	v_pk_fma_f32 v[36:37], v[28:29], 0.5, v[92:93] op_sel_hi:[1,0,1]
	v_pk_fma_f32 v[40:41], v[20:21], 0.5, v[84:85] op_sel_hi:[1,0,1]
	v_fmac_f32_e32 v18, v39, v39
	v_fmac_f32_e32 v19, v43, v43
	v_fmac_f32_e32 v18, v36, v36
	v_fmac_f32_e32 v19, v40, v40
	v_fmac_f32_e32 v18, v37, v37
	v_fmac_f32_e32 v19, v41, v41
	v_add_f32_e32 v21, v18, v19
	v_cvt_pk_bf16_f32 v27, v32, v33
	ds_bpermute_b32 v32, v213, v21
	s_waitcnt lgkmcnt(1)
	v_lshlrev_b64 v[34:35], 11, v[116:117]
	v_lshl_add_u64 v[18:19], s[68:69], 0, v[34:35]
	v_cvt_pk_bf16_f32 v26, v30, v31
	v_lshl_add_u64 v[30:31], v[194:195], 1, v[18:19]
	s_waitcnt lgkmcnt(0)
	v_add_f32_e32 v18, v21, v32
	ds_bpermute_b32 v19, v122, v18
	v_cvt_pk_bf16_f32 v28, v38, v39
	v_cvt_pk_bf16_f32 v29, v36, v37
	v_cvt_pk_bf16_f32 v20, v22, v23
	v_cvt_pk_bf16_f32 v21, v24, v25
	v_cvt_pk_bf16_f32 v22, v42, v43
	v_cvt_pk_bf16_f32 v23, v40, v41
	global_store_dwordx4 v[30:31], v[26:29], off nt
	global_store_dwordx4 v[30:31], v[20:23], off offset:256 nt
	s_and_saveexec_b64 s[22:23], s[2:3]
	s_cbranch_execz .LBB0_134
	s_waitcnt lgkmcnt(0)
	v_add_f32_e32 v20, v18, v19
	v_lshl_add_u64 v[18:19], v[116:117], 2, s[14:15]
	global_atomic_add_f32 v[18:19], v20, off
.LBB0_134:
	s_or_b64 exec, exec, s[22:23]
	s_waitcnt vmcnt(8)
	v_pk_fma_f32 v[14:15], v[14:15], 0.5, v[78:79] op_sel_hi:[1,0,1]
	s_waitcnt vmcnt(6)
	v_pk_fma_f32 v[6:7], v[6:7], 0.5, v[70:71] op_sel_hi:[1,0,1]
	v_pk_fma_f32 v[26:27], v[2:3], 0.5, v[66:67] op_sel_hi:[1,0,1]
	v_mul_f32_e32 v2, v15, v15
	v_mul_f32_e32 v3, v7, v7
	v_pk_fma_f32 v[16:17], v[16:17], 0.5, v[80:81] op_sel_hi:[1,0,1]
	v_pk_fma_f32 v[8:9], v[8:9], 0.5, v[72:73] op_sel_hi:[1,0,1]
	v_fmac_f32_e32 v2, v14, v14
	v_fmac_f32_e32 v3, v6, v6
	v_fmac_f32_e32 v2, v16, v16
	v_fmac_f32_e32 v3, v8, v8
	v_pk_fma_f32 v[22:23], v[10:11], 0.5, v[74:75] op_sel_hi:[1,0,1]
	v_fmac_f32_e32 v2, v17, v17
	v_fmac_f32_e32 v3, v9, v9
	v_fmac_f32_e32 v2, v22, v22
	v_fmac_f32_e32 v3, v26, v26
	v_pk_fma_f32 v[20:21], v[12:13], 0.5, v[76:77] op_sel_hi:[1,0,1]
	v_pk_fma_f32 v[24:25], v[4:5], 0.5, v[68:69] op_sel_hi:[1,0,1]
	v_fmac_f32_e32 v2, v23, v23
	v_fmac_f32_e32 v3, v27, v27
	v_fmac_f32_e32 v2, v20, v20
	v_fmac_f32_e32 v3, v24, v24
	v_fmac_f32_e32 v2, v21, v21
	v_fmac_f32_e32 v3, v25, v25
	v_add_f32_e32 v5, v2, v3
	v_cvt_pk_bf16_f32 v11, v16, v17
	ds_bpermute_b32 v16, v213, v5
	s_waitcnt lgkmcnt(1)
	v_lshlrev_b64 v[18:19], 11, v[114:115]
	v_lshl_add_u64 v[2:3], s[68:69], 0, v[18:19]
	v_cvt_pk_bf16_f32 v10, v14, v15
	v_lshl_add_u64 v[14:15], v[194:195], 1, v[2:3]
	s_waitcnt lgkmcnt(0)
	v_add_f32_e32 v2, v5, v16
	ds_bpermute_b32 v3, v122, v2
	v_cvt_pk_bf16_f32 v12, v22, v23
	v_cvt_pk_bf16_f32 v13, v20, v21
	v_cvt_pk_bf16_f32 v4, v6, v7
	v_cvt_pk_bf16_f32 v5, v8, v9
	v_cvt_pk_bf16_f32 v6, v26, v27
	v_cvt_pk_bf16_f32 v7, v24, v25
	global_store_dwordx4 v[14:15], v[10:13], off nt
	global_store_dwordx4 v[14:15], v[4:7], off offset:256 nt
	s_and_saveexec_b64 s[22:23], s[2:3]
	s_cbranch_execz .LBB0_107
	s_waitcnt lgkmcnt(0)
	v_add_f32_e32 v4, v2, v3
	v_lshl_add_u64 v[2:3], v[114:115], 2, s[14:15]
	global_atomic_add_f32 v[2:3], v4, off
	s_branch .LBB0_107

.LBB0_211:
	s_waitcnt lgkmcnt(0)
	v_pk_mul_f32 v[128:129], v[128:129], v[152:153] op_sel_hi:[1,0]
	v_pk_mul_f32 v[126:127], v[126:127], v[152:153] op_sel_hi:[1,0]
	v_pk_mul_f32 v[168:169], v[124:125], v[152:153] op_sel_hi:[1,0]
	v_pk_mul_f32 v[124:125], v[122:123], v[152:153] op_sel_hi:[1,0]
	v_cvt_pk_bf16_f32 v122, v126, v127
	v_cvt_pk_bf16_f32 v123, v128, v129
	v_cvt_pk_bf16_f32 v124, v124, v125
	v_cvt_pk_bf16_f32 v125, v168, v169
	global_store_dwordx4 v[158:159], v[122:125], off nt
	s_andn2_b64 vcc, exec, s[34:35]
	s_nop 0
	v_cndmask_b32_e64 v122, 0, 1, s[34:35]
	v_cmp_ne_u32_e64 s[4:5], 1, v122
	s_mov_b64 s[34:35], -1
	s_cbranch_vccnz .LBB0_213
	v_mov_b32_e32 v138, v148
	v_lshl_add_u64 v[122:123], v[138:139], 1, v[154:155]
	v_lshl_add_u64 v[122:123], v[122:123], 0, s[22:23]
	s_mov_b64 s[34:35], 0

.LBB0_215:
	v_mov_b32_e32 v153, v152
	v_mov_b32_e32 v124, v152
	v_mov_b32_e32 v125, v152
	v_pk_mul_f32 v[120:121], v[120:121], v[124:125]
	v_pk_mul_f32 v[118:119], v[118:119], v[152:153]
	v_pk_mul_f32 v[124:125], v[116:117], v[124:125]
	v_pk_mul_f32 v[116:117], v[114:115], v[152:153]
	v_cvt_pk_bf16_f32 v114, v118, v119
	v_cvt_pk_bf16_f32 v115, v120, v121
	v_cvt_pk_bf16_f32 v116, v116, v117
	v_cvt_pk_bf16_f32 v117, v124, v125
	global_store_dwordx4 v[122:123], v[114:117], off nt
	ds_read_b32 v114, v167 offset:64
	v_or_b32_e32 v118, 16, v150
	v_ashrrev_i32_e32 v119, 31, v118
	v_lshlrev_b64 v[116:117], 11, v[118:119]
	s_mov_b64 s[34:35], -1
	s_and_b64 vcc, exec, s[4:5]
	v_lshl_add_u64 v[116:117], s[8:9], 0, v[116:117]
	s_cbranch_vccnz .LBB0_217
	v_mov_b32_e32 v138, v148
	v_lshl_add_u64 v[120:121], v[138:139], 1, v[116:117]
	v_lshl_add_u64 v[120:121], v[120:121], 0, s[20:21]
	s_mov_b64 s[34:35], 0

.LBB0_219:
	s_waitcnt lgkmcnt(0)
	v_pk_mul_f32 v[112:113], v[112:113], v[114:115] op_sel_hi:[1,0]
	v_pk_mul_f32 v[110:111], v[110:111], v[114:115] op_sel_hi:[1,0]
	v_pk_mul_f32 v[122:123], v[108:109], v[114:115] op_sel_hi:[1,0]
	v_pk_mul_f32 v[108:109], v[106:107], v[114:115] op_sel_hi:[1,0]
	v_cvt_pk_bf16_f32 v106, v110, v111
	v_cvt_pk_bf16_f32 v107, v112, v113
	v_cvt_pk_bf16_f32 v108, v108, v109
	v_cvt_pk_bf16_f32 v109, v122, v123
	s_and_b64 vcc, exec, s[4:5]
	s_mov_b64 s[34:35], -1
	global_store_dwordx4 v[120:121], v[106:109], off nt
	s_cbranch_vccnz .LBB0_221
	v_mov_b32_e32 v138, v148
	v_lshl_add_u64 v[106:107], v[138:139], 1, v[116:117]
	v_lshl_add_u64 v[106:107], v[106:107], 0, s[22:23]
	s_mov_b64 s[34:35], 0

.LBB0_223:
	v_mov_b32_e32 v115, v114
	v_mov_b32_e32 v108, v114
	v_mov_b32_e32 v109, v114
	v_pk_mul_f32 v[104:105], v[104:105], v[108:109]
	v_pk_mul_f32 v[102:103], v[102:103], v[114:115]
	v_pk_mul_f32 v[108:109], v[100:101], v[108:109]
	v_pk_mul_f32 v[100:101], v[98:99], v[114:115]
	v_cvt_pk_bf16_f32 v98, v102, v103
	v_cvt_pk_bf16_f32 v99, v104, v105
	v_cvt_pk_bf16_f32 v100, v100, v101
	v_cvt_pk_bf16_f32 v101, v108, v109
	global_store_dwordx4 v[106:107], v[98:101], off nt
	ds_read_b32 v98, v167 offset:128
	v_or_b32_e32 v102, 32, v150
	v_ashrrev_i32_e32 v103, 31, v102
	v_lshlrev_b64 v[100:101], 11, v[102:103]
	s_mov_b64 s[34:35], -1
	s_and_b64 vcc, exec, s[4:5]
	v_lshl_add_u64 v[100:101], s[8:9], 0, v[100:101]
	s_cbranch_vccnz .LBB0_225
	v_mov_b32_e32 v138, v148
	v_lshl_add_u64 v[104:105], v[138:139], 1, v[100:101]
	v_lshl_add_u64 v[104:105], v[104:105], 0, s[20:21]
	s_mov_b64 s[34:35], 0

.LBB0_227:
	s_waitcnt lgkmcnt(0)
	v_pk_mul_f32 v[96:97], v[96:97], v[98:99] op_sel_hi:[1,0]
	v_pk_mul_f32 v[94:95], v[94:95], v[98:99] op_sel_hi:[1,0]
	v_pk_mul_f32 v[106:107], v[92:93], v[98:99] op_sel_hi:[1,0]
	v_pk_mul_f32 v[92:93], v[90:91], v[98:99] op_sel_hi:[1,0]
	v_cvt_pk_bf16_f32 v90, v94, v95
	v_cvt_pk_bf16_f32 v91, v96, v97
	v_cvt_pk_bf16_f32 v92, v92, v93
	v_cvt_pk_bf16_f32 v93, v106, v107
	s_and_b64 vcc, exec, s[4:5]
	s_mov_b64 s[34:35], -1
	global_store_dwordx4 v[104:105], v[90:93], off nt
	s_cbranch_vccnz .LBB0_229
	v_mov_b32_e32 v138, v148
	v_lshl_add_u64 v[90:91], v[138:139], 1, v[100:101]
	v_lshl_add_u64 v[90:91], v[90:91], 0, s[22:23]
	s_mov_b64 s[34:35], 0

.LBB0_231:
	v_mov_b32_e32 v99, v98
	v_mov_b32_e32 v92, v98
	v_mov_b32_e32 v93, v98
	v_pk_mul_f32 v[88:89], v[88:89], v[92:93]
	v_pk_mul_f32 v[86:87], v[86:87], v[98:99]
	v_pk_mul_f32 v[92:93], v[84:85], v[92:93]
	v_pk_mul_f32 v[84:85], v[82:83], v[98:99]
	v_cvt_pk_bf16_f32 v82, v86, v87
	v_cvt_pk_bf16_f32 v83, v88, v89
	v_cvt_pk_bf16_f32 v84, v84, v85
	v_cvt_pk_bf16_f32 v85, v92, v93
	global_store_dwordx4 v[90:91], v[82:85], off nt
	ds_read_b32 v82, v167 offset:192
	v_or_b32_e32 v86, 48, v150
	v_ashrrev_i32_e32 v87, 31, v86
	v_lshlrev_b64 v[84:85], 11, v[86:87]
	s_mov_b64 s[34:35], -1
	s_and_b64 vcc, exec, s[4:5]
	v_lshl_add_u64 v[84:85], s[8:9], 0, v[84:85]
	s_cbranch_vccnz .LBB0_233
	v_mov_b32_e32 v138, v148
	v_lshl_add_u64 v[88:89], v[138:139], 1, v[84:85]
	v_lshl_add_u64 v[88:89], v[88:89], 0, s[20:21]
	s_mov_b64 s[34:35], 0

.LBB0_235:
	s_waitcnt lgkmcnt(0)
	v_pk_mul_f32 v[80:81], v[80:81], v[82:83] op_sel_hi:[1,0]
	v_pk_mul_f32 v[78:79], v[78:79], v[82:83] op_sel_hi:[1,0]
	v_pk_mul_f32 v[90:91], v[76:77], v[82:83] op_sel_hi:[1,0]
	v_pk_mul_f32 v[76:77], v[74:75], v[82:83] op_sel_hi:[1,0]
	v_cvt_pk_bf16_f32 v74, v78, v79
	v_cvt_pk_bf16_f32 v75, v80, v81
	v_cvt_pk_bf16_f32 v76, v76, v77
	v_cvt_pk_bf16_f32 v77, v90, v91
	s_and_b64 vcc, exec, s[4:5]
	s_mov_b64 s[34:35], -1
	global_store_dwordx4 v[88:89], v[74:77], off nt
	s_cbranch_vccnz .LBB0_237
	v_mov_b32_e32 v138, v148
	v_lshl_add_u64 v[74:75], v[138:139], 1, v[84:85]
	v_lshl_add_u64 v[74:75], v[74:75], 0, s[22:23]
	s_mov_b64 s[34:35], 0

.LBB0_239:
	v_mov_b32_e32 v83, v82
	v_mov_b32_e32 v76, v82
	v_mov_b32_e32 v77, v82
	v_pk_mul_f32 v[72:73], v[72:73], v[76:77]
	v_pk_mul_f32 v[70:71], v[70:71], v[82:83]
	v_pk_mul_f32 v[76:77], v[68:69], v[76:77]
	v_pk_mul_f32 v[68:69], v[66:67], v[82:83]
	v_cvt_pk_bf16_f32 v66, v70, v71
	v_cvt_pk_bf16_f32 v67, v72, v73
	v_cvt_pk_bf16_f32 v68, v68, v69
	v_cvt_pk_bf16_f32 v69, v76, v77
	global_store_dwordx4 v[74:75], v[66:69], off nt
	ds_read_b32 v66, v167 offset:512
	v_add_u32_e32 v70, 0x80, v150
	v_ashrrev_i32_e32 v71, 31, v70
	v_lshlrev_b64 v[68:69], 11, v[70:71]
	s_mov_b64 s[34:35], -1
	s_and_b64 vcc, exec, s[4:5]
	v_lshl_add_u64 v[68:69], s[8:9], 0, v[68:69]
	s_cbranch_vccnz .LBB0_241
	v_mov_b32_e32 v138, v148
	v_lshl_add_u64 v[72:73], v[138:139], 1, v[68:69]
	v_lshl_add_u64 v[72:73], v[72:73], 0, s[20:21]
	s_mov_b64 s[34:35], 0

.LBB0_243:
	s_waitcnt lgkmcnt(0)
	v_pk_mul_f32 v[64:65], v[64:65], v[66:67] op_sel_hi:[1,0]
	v_pk_mul_f32 v[62:63], v[62:63], v[66:67] op_sel_hi:[1,0]
	v_pk_mul_f32 v[74:75], v[60:61], v[66:67] op_sel_hi:[1,0]
	v_pk_mul_f32 v[60:61], v[58:59], v[66:67] op_sel_hi:[1,0]
	v_cvt_pk_bf16_f32 v58, v62, v63
	v_cvt_pk_bf16_f32 v59, v64, v65
	v_cvt_pk_bf16_f32 v60, v60, v61
	v_cvt_pk_bf16_f32 v61, v74, v75
	s_and_b64 vcc, exec, s[4:5]
	s_mov_b64 s[34:35], -1
	global_store_dwordx4 v[72:73], v[58:61], off nt
	s_cbranch_vccnz .LBB0_245
	v_mov_b32_e32 v138, v148
	v_lshl_add_u64 v[58:59], v[138:139], 1, v[68:69]
	v_lshl_add_u64 v[58:59], v[58:59], 0, s[22:23]
	s_mov_b64 s[34:35], 0

.LBB0_247:
	v_mov_b32_e32 v67, v66
	v_mov_b32_e32 v60, v66
	v_mov_b32_e32 v61, v66
	v_pk_mul_f32 v[56:57], v[56:57], v[60:61]
	v_pk_mul_f32 v[54:55], v[54:55], v[66:67]
	v_pk_mul_f32 v[60:61], v[52:53], v[60:61]
	v_pk_mul_f32 v[52:53], v[50:51], v[66:67]
	v_cvt_pk_bf16_f32 v50, v54, v55
	v_cvt_pk_bf16_f32 v51, v56, v57
	v_cvt_pk_bf16_f32 v52, v52, v53
	v_cvt_pk_bf16_f32 v53, v60, v61
	global_store_dwordx4 v[58:59], v[50:53], off nt
	ds_read_b32 v50, v167 offset:576
	v_add_u32_e32 v54, 0x90, v150
	v_ashrrev_i32_e32 v55, 31, v54
	v_lshlrev_b64 v[52:53], 11, v[54:55]
	s_mov_b64 s[34:35], -1
	s_and_b64 vcc, exec, s[4:5]
	v_lshl_add_u64 v[52:53], s[8:9], 0, v[52:53]
	s_cbranch_vccnz .LBB0_249
	v_mov_b32_e32 v138, v148
	v_lshl_add_u64 v[56:57], v[138:139], 1, v[52:53]
	v_lshl_add_u64 v[56:57], v[56:57], 0, s[20:21]
	s_mov_b64 s[34:35], 0

.LBB0_251:
	s_waitcnt lgkmcnt(0)
	v_pk_mul_f32 v[48:49], v[48:49], v[50:51] op_sel_hi:[1,0]
	v_pk_mul_f32 v[46:47], v[46:47], v[50:51] op_sel_hi:[1,0]
	v_pk_mul_f32 v[58:59], v[44:45], v[50:51] op_sel_hi:[1,0]
	v_pk_mul_f32 v[44:45], v[42:43], v[50:51] op_sel_hi:[1,0]
	v_cvt_pk_bf16_f32 v42, v46, v47
	v_cvt_pk_bf16_f32 v43, v48, v49
	v_cvt_pk_bf16_f32 v44, v44, v45
	v_cvt_pk_bf16_f32 v45, v58, v59
	s_and_b64 vcc, exec, s[4:5]
	s_mov_b64 s[34:35], -1
	global_store_dwordx4 v[56:57], v[42:45], off nt
	s_cbranch_vccnz .LBB0_253
	v_mov_b32_e32 v138, v148
	v_lshl_add_u64 v[42:43], v[138:139], 1, v[52:53]
	v_lshl_add_u64 v[42:43], v[42:43], 0, s[22:23]
	s_mov_b64 s[34:35], 0

.LBB0_255:
	v_mov_b32_e32 v51, v50
	v_mov_b32_e32 v44, v50
	v_mov_b32_e32 v45, v50
	v_pk_mul_f32 v[40:41], v[40:41], v[44:45]
	v_pk_mul_f32 v[38:39], v[38:39], v[50:51]
	v_pk_mul_f32 v[44:45], v[36:37], v[44:45]
	v_pk_mul_f32 v[36:37], v[34:35], v[50:51]
	v_cvt_pk_bf16_f32 v34, v38, v39
	v_cvt_pk_bf16_f32 v35, v40, v41
	v_cvt_pk_bf16_f32 v36, v36, v37
	v_cvt_pk_bf16_f32 v37, v44, v45
	global_store_dwordx4 v[42:43], v[34:37], off nt
	ds_read_b32 v34, v167 offset:640
	v_add_u32_e32 v38, 0xa0, v150
	v_ashrrev_i32_e32 v39, 31, v38
	v_lshlrev_b64 v[36:37], 11, v[38:39]
	s_mov_b64 s[34:35], -1
	s_and_b64 vcc, exec, s[4:5]
	v_lshl_add_u64 v[36:37], s[8:9], 0, v[36:37]
	s_cbranch_vccnz .LBB0_257
	v_mov_b32_e32 v138, v148
	v_lshl_add_u64 v[40:41], v[138:139], 1, v[36:37]
	v_lshl_add_u64 v[40:41], v[40:41], 0, s[20:21]
	s_mov_b64 s[34:35], 0

.LBB0_259:
	s_waitcnt lgkmcnt(0)
	v_pk_mul_f32 v[32:33], v[32:33], v[34:35] op_sel_hi:[1,0]
	v_pk_mul_f32 v[30:31], v[30:31], v[34:35] op_sel_hi:[1,0]
	v_pk_mul_f32 v[42:43], v[28:29], v[34:35] op_sel_hi:[1,0]
	v_pk_mul_f32 v[28:29], v[26:27], v[34:35] op_sel_hi:[1,0]
	v_cvt_pk_bf16_f32 v26, v30, v31
	v_cvt_pk_bf16_f32 v27, v32, v33
	v_cvt_pk_bf16_f32 v28, v28, v29
	v_cvt_pk_bf16_f32 v29, v42, v43
	s_and_b64 vcc, exec, s[4:5]
	s_mov_b64 s[34:35], -1
	global_store_dwordx4 v[40:41], v[26:29], off nt
	s_cbranch_vccnz .LBB0_261
	v_mov_b32_e32 v138, v148
	v_lshl_add_u64 v[26:27], v[138:139], 1, v[36:37]
	v_lshl_add_u64 v[26:27], v[26:27], 0, s[22:23]
	s_mov_b64 s[34:35], 0

.LBB0_263:
	v_mov_b32_e32 v35, v34
	v_mov_b32_e32 v28, v34
	v_mov_b32_e32 v29, v34
	v_pk_mul_f32 v[24:25], v[24:25], v[28:29]
	v_pk_mul_f32 v[22:23], v[22:23], v[34:35]
	v_pk_mul_f32 v[28:29], v[20:21], v[28:29]
	v_pk_mul_f32 v[20:21], v[18:19], v[34:35]
	v_cvt_pk_bf16_f32 v18, v22, v23
	v_cvt_pk_bf16_f32 v19, v24, v25
	v_cvt_pk_bf16_f32 v20, v20, v21
	v_cvt_pk_bf16_f32 v21, v28, v29
	global_store_dwordx4 v[26:27], v[18:21], off nt
	ds_read_b32 v18, v167 offset:704
	v_add_u32_e32 v22, 0xb0, v150
	v_ashrrev_i32_e32 v23, 31, v22
	v_lshlrev_b64 v[20:21], 11, v[22:23]
	s_mov_b64 s[34:35], -1
	s_and_b64 vcc, exec, s[4:5]
	v_lshl_add_u64 v[20:21], s[8:9], 0, v[20:21]
	s_cbranch_vccnz .LBB0_265
	v_mov_b32_e32 v138, v148
	v_lshl_add_u64 v[24:25], v[138:139], 1, v[20:21]
	v_lshl_add_u64 v[24:25], v[24:25], 0, s[20:21]
	s_mov_b64 s[34:35], 0

.LBB0_267:
	s_waitcnt lgkmcnt(0)
	v_pk_mul_f32 v[16:17], v[16:17], v[18:19] op_sel_hi:[1,0]
	v_pk_mul_f32 v[14:15], v[14:15], v[18:19] op_sel_hi:[1,0]
	v_pk_mul_f32 v[26:27], v[12:13], v[18:19] op_sel_hi:[1,0]
	v_pk_mul_f32 v[12:13], v[10:11], v[18:19] op_sel_hi:[1,0]
	v_cvt_pk_bf16_f32 v10, v14, v15
	v_cvt_pk_bf16_f32 v11, v16, v17
	v_cvt_pk_bf16_f32 v12, v12, v13
	v_cvt_pk_bf16_f32 v13, v26, v27
	s_and_b64 vcc, exec, s[4:5]
	s_mov_b64 s[4:5], -1
	global_store_dwordx4 v[24:25], v[10:13], off nt
	s_cbranch_vccnz .LBB0_269
	v_mov_b32_e32 v138, v148
	v_lshl_add_u64 v[10:11], v[138:139], 1, v[20:21]
	v_lshl_add_u64 v[10:11], v[10:11], 0, s[22:23]
	s_mov_b64 s[4:5], 0

.Lgemm_epi3:
	v_lshl_or_b32 v170, s22, 8, v190
	v_lshl_add_u32 v174, s20, 8, v188
	v_ashrrev_i32_e32 v171, 31, v170
	v_lshlrev_b64 v[204:205], 1, v[170:171]
	v_ashrrev_i32_e32 v175, 31, v174
	v_lshl_add_u64 v[172:173], s[68:69], 0, v[204:205]
	v_lshlrev_b64 v[206:207], 11, v[174:175]
	v_lshl_add_u64 v[130:131], v[172:173], 0, v[206:207]
	global_load_dwordx4 v[196:199], v[130:131], off
	global_load_dwordx4 v[200:203], v[130:131], off offset:256
	v_or_b32_e32 v184, 16, v174
	v_or_b32_e32 v180, 32, v174
	v_or_b32_e32 v176, 48, v174
	v_ashrrev_i32_e32 v185, 31, v184
	v_ashrrev_i32_e32 v181, 31, v180
	v_ashrrev_i32_e32 v177, 31, v176
	v_lshlrev_b64 v[186:187], 11, v[184:185]
	v_lshlrev_b64 v[182:183], 11, v[180:181]
	v_lshlrev_b64 v[178:179], 11, v[176:177]
	v_lshl_add_u64 v[130:131], v[172:173], 0, v[186:187]
	v_lshl_add_u64 v[132:133], v[172:173], 0, v[182:183]
	v_lshl_add_u64 v[208:209], v[172:173], 0, v[178:179]
	global_load_dwordx4 v[150:153], v[130:131], off
	global_load_dwordx4 v[146:149], v[130:131], off offset:256
	global_load_dwordx4 v[142:145], v[132:133], off
	global_load_dwordx4 v[138:141], v[132:133], off offset:256
	global_load_dwordx4 v[134:137], v[208:209], off
	s_nop 0
	global_load_dwordx4 v[130:133], v[208:209], off offset:256
	v_lshl_add_u64 v[206:207], s[68:69], 0, v[206:207]
	v_and_b32_e32 v208, 64, v194
	v_lshl_add_u64 v[204:205], v[206:207], 0, v[204:205]
	v_xor_b32_e32 v195, 16, v194
	v_add_u32_e32 v208, 64, v208
	v_xor_b32_e32 v209, 32, v194
	v_cmp_lt_i32_e32 vcc, v195, v208
	s_waitcnt vmcnt(0)
	v_lshlrev_b32_e32 v206, 16, v196
	v_and_b32_e32 v207, 0xffff0000, v196
	v_lshlrev_b32_e32 v210, 16, v200
	v_and_b32_e32 v211, 0xffff0000, v200
	v_lshlrev_b32_e32 v196, 16, v197
	v_and_b32_e32 v197, 0xffff0000, v197
	v_lshlrev_b32_e32 v212, 16, v202
	v_and_b32_e32 v213, 0xffff0000, v202
	v_lshlrev_b32_e32 v202, 16, v203
	v_and_b32_e32 v203, 0xffff0000, v203
	v_pk_add_f32 v[126:127], v[126:127], v[206:207]
	v_pk_add_f32 v[118:119], v[118:119], v[210:211]
	v_lshlrev_b32_e32 v200, 16, v201
	v_and_b32_e32 v201, 0xffff0000, v201
	v_pk_add_f32 v[128:129], v[128:129], v[196:197]
	v_pk_add_f32 v[196:197], v[116:117], v[202:203]
	v_mul_f32_e32 v116, v127, v127
	v_mul_f32_e32 v117, v119, v119
	v_cndmask_b32_e32 v195, v194, v195, vcc
	v_cmp_lt_i32_e32 vcc, v209, v208
	v_pk_add_f32 v[120:121], v[120:121], v[200:201]
	v_fmac_f32_e32 v116, v126, v126
	v_fmac_f32_e32 v117, v118, v118
	v_cndmask_b32_e32 v214, v194, v209, vcc
	v_lshlrev_b32_e32 v208, 16, v198
	v_and_b32_e32 v209, 0xffff0000, v198
	v_lshlrev_b32_e32 v198, 16, v199
	v_and_b32_e32 v199, 0xffff0000, v199
	v_fmac_f32_e32 v116, v128, v128
	v_fmac_f32_e32 v117, v120, v120
	v_pk_add_f32 v[124:125], v[124:125], v[198:199]
	v_pk_add_f32 v[122:123], v[122:123], v[208:209]
	v_pk_add_f32 v[198:199], v[114:115], v[212:213]
	v_fmac_f32_e32 v116, v129, v129
	v_fmac_f32_e32 v117, v121, v121
	v_fmac_f32_e32 v116, v122, v122
	v_fmac_f32_e32 v117, v198, v198
	v_fmac_f32_e32 v116, v123, v123
	v_fmac_f32_e32 v117, v199, v199
	v_fmac_f32_e32 v116, v124, v124
	v_fmac_f32_e32 v117, v196, v196
	v_fmac_f32_e32 v116, v125, v125
	v_fmac_f32_e32 v117, v197, v197
	v_lshlrev_b32_e32 v195, 2, v195
	v_cvt_pk_bf16_f32 v114, v126, v127
	v_add_f32_e32 v126, v116, v117
	ds_bpermute_b32 v127, v195, v126
	v_cvt_pk_bf16_f32 v115, v128, v129
	v_cvt_pk_bf16_f32 v116, v122, v123
	v_cvt_pk_bf16_f32 v117, v124, v125
	global_store_dwordx4 v[204:205], v[114:117], off nt
	v_cvt_pk_bf16_f32 v118, v118, v119
	v_cvt_pk_bf16_f32 v119, v120, v121
	s_waitcnt lgkmcnt(0)
	v_add_f32_e32 v115, v126, v127
	v_lshlrev_b32_e32 v114, 2, v214
	ds_bpermute_b32 v116, v114, v115
	v_cvt_pk_bf16_f32 v120, v198, v199
	v_cvt_pk_bf16_f32 v121, v196, v197
	global_store_dwordx4 v[204:205], v[118:121], off offset:256 nt
	s_and_saveexec_b64 s[20:21], s[2:3]
	s_cbranch_execz .LBB0_589
	s_waitcnt lgkmcnt(0)
	v_add_f32_e32 v115, v115, v116
	v_lshl_add_u64 v[116:117], v[174:175], 2, s[6:7]
	global_atomic_add_f32 v[116:117], v115, off
.LBB0_589:
	s_or_b64 exec, exec, s[20:21]
	v_lshlrev_b32_e32 v118, 16, v151
	v_and_b32_e32 v119, 0xffff0000, v151
	v_lshlrev_b32_e32 v120, 16, v152
	v_and_b32_e32 v121, 0xffff0000, v152
	s_waitcnt lgkmcnt(0)
	v_lshlrev_b32_e32 v116, 16, v150
	v_and_b32_e32 v117, 0xffff0000, v150
	v_lshlrev_b32_e32 v122, 16, v153
	v_and_b32_e32 v123, 0xffff0000, v153
	v_pk_add_f32 v[112:113], v[112:113], v[118:119]
	v_pk_add_f32 v[118:119], v[106:107], v[120:121]
	v_lshlrev_b32_e32 v120, 16, v146
	v_and_b32_e32 v121, 0xffff0000, v146
	v_pk_add_f32 v[110:111], v[110:111], v[116:117]
	v_pk_add_f32 v[116:117], v[108:109], v[122:123]
	v_lshlrev_b32_e32 v122, 16, v147
	v_and_b32_e32 v123, 0xffff0000, v147
	v_lshlrev_b32_e32 v124, 16, v148
	v_and_b32_e32 v125, 0xffff0000, v148
	v_pk_add_f32 v[102:103], v[102:103], v[120:121]
	v_pk_add_f32 v[104:105], v[104:105], v[122:123]
	v_pk_add_f32 v[122:123], v[98:99], v[124:125]
	v_mul_f32_e32 v98, v111, v111
	v_mul_f32_e32 v99, v103, v103
	v_fmac_f32_e32 v98, v110, v110
	v_fmac_f32_e32 v99, v102, v102
	v_fmac_f32_e32 v98, v112, v112
	v_fmac_f32_e32 v99, v104, v104
	v_fmac_f32_e32 v98, v113, v113
	v_fmac_f32_e32 v99, v105, v105
	v_lshlrev_b32_e32 v126, 16, v149
	v_and_b32_e32 v127, 0xffff0000, v149
	v_fmac_f32_e32 v98, v118, v118
	v_fmac_f32_e32 v99, v122, v122
	v_pk_add_f32 v[120:121], v[100:101], v[126:127]
	v_fmac_f32_e32 v98, v119, v119
	v_fmac_f32_e32 v99, v123, v123
	v_fmac_f32_e32 v98, v116, v116
	v_fmac_f32_e32 v99, v120, v120
	v_fmac_f32_e32 v98, v117, v117
	v_fmac_f32_e32 v99, v121, v121
	v_add_f32_e32 v101, v98, v99
	v_cvt_pk_bf16_f32 v107, v112, v113
	ds_bpermute_b32 v112, v195, v101
	v_lshl_add_u64 v[98:99], s[68:69], 0, v[186:187]
	v_cvt_pk_bf16_f32 v106, v110, v111
	v_lshl_add_u64 v[110:111], v[170:171], 1, v[98:99]
	v_cvt_pk_bf16_f32 v108, v118, v119
	s_waitcnt lgkmcnt(0)
	v_add_f32_e32 v98, v101, v112
	ds_bpermute_b32 v99, v114, v98
	v_cvt_pk_bf16_f32 v109, v116, v117
	v_cvt_pk_bf16_f32 v100, v102, v103
	v_cvt_pk_bf16_f32 v101, v104, v105
	v_cvt_pk_bf16_f32 v102, v122, v123
	v_cvt_pk_bf16_f32 v103, v120, v121
	global_store_dwordx4 v[110:111], v[106:109], off nt
	global_store_dwordx4 v[110:111], v[100:103], off offset:256 nt
	s_and_saveexec_b64 s[20:21], s[2:3]
	s_cbranch_execz .LBB0_591
	s_waitcnt lgkmcnt(0)
	v_add_f32_e32 v100, v98, v99
	v_lshl_add_u64 v[98:99], v[184:185], 2, s[6:7]
	global_atomic_add_f32 v[98:99], v100, off
.LBB0_591:
	s_or_b64 exec, exec, s[20:21]
	v_lshlrev_b32_e32 v100, 16, v143
	v_and_b32_e32 v101, 0xffff0000, v143
	v_lshlrev_b32_e32 v102, 16, v144
	v_and_b32_e32 v103, 0xffff0000, v144
	v_lshlrev_b32_e32 v98, 16, v142
	s_waitcnt lgkmcnt(0)
	v_and_b32_e32 v99, 0xffff0000, v142
	v_lshlrev_b32_e32 v104, 16, v145
	v_and_b32_e32 v105, 0xffff0000, v145
	v_pk_add_f32 v[96:97], v[96:97], v[100:101]
	v_pk_add_f32 v[100:101], v[90:91], v[102:103]
	v_lshlrev_b32_e32 v102, 16, v138
	v_and_b32_e32 v103, 0xffff0000, v138
	v_pk_add_f32 v[94:95], v[94:95], v[98:99]
	v_pk_add_f32 v[98:99], v[92:93], v[104:105]
	v_lshlrev_b32_e32 v104, 16, v139
	v_and_b32_e32 v105, 0xffff0000, v139
	v_lshlrev_b32_e32 v106, 16, v140
	v_and_b32_e32 v107, 0xffff0000, v140
	v_pk_add_f32 v[86:87], v[86:87], v[102:103]
	v_pk_add_f32 v[88:89], v[88:89], v[104:105]
	v_pk_add_f32 v[104:105], v[82:83], v[106:107]
	v_mul_f32_e32 v82, v95, v95
	v_mul_f32_e32 v83, v87, v87
	v_fmac_f32_e32 v82, v94, v94
	v_fmac_f32_e32 v83, v86, v86
	v_fmac_f32_e32 v82, v96, v96
	v_fmac_f32_e32 v83, v88, v88
	v_fmac_f32_e32 v82, v97, v97
	v_fmac_f32_e32 v83, v89, v89
	v_lshlrev_b32_e32 v108, 16, v141
	v_and_b32_e32 v109, 0xffff0000, v141
	v_fmac_f32_e32 v82, v100, v100
	v_fmac_f32_e32 v83, v104, v104
	v_pk_add_f32 v[102:103], v[84:85], v[108:109]
	v_fmac_f32_e32 v82, v101, v101
	v_fmac_f32_e32 v83, v105, v105
	v_fmac_f32_e32 v82, v98, v98
	v_fmac_f32_e32 v83, v102, v102
	v_fmac_f32_e32 v82, v99, v99
	v_fmac_f32_e32 v83, v103, v103
	v_add_f32_e32 v85, v82, v83
	v_cvt_pk_bf16_f32 v91, v96, v97
	ds_bpermute_b32 v96, v195, v85
	v_lshl_add_u64 v[82:83], s[68:69], 0, v[182:183]
	v_cvt_pk_bf16_f32 v90, v94, v95
	v_lshl_add_u64 v[94:95], v[170:171], 1, v[82:83]
	v_cvt_pk_bf16_f32 v92, v100, v101
	s_waitcnt lgkmcnt(0)
	v_add_f32_e32 v82, v85, v96
	ds_bpermute_b32 v83, v114, v82
	v_cvt_pk_bf16_f32 v93, v98, v99
	v_cvt_pk_bf16_f32 v84, v86, v87
	v_cvt_pk_bf16_f32 v85, v88, v89
	v_cvt_pk_bf16_f32 v86, v104, v105
	v_cvt_pk_bf16_f32 v87, v102, v103
	global_store_dwordx4 v[94:95], v[90:93], off nt
	global_store_dwordx4 v[94:95], v[84:87], off offset:256 nt
	s_and_saveexec_b64 s[20:21], s[2:3]
	s_cbranch_execz .LBB0_593
	s_waitcnt lgkmcnt(0)
	v_add_f32_e32 v84, v82, v83
	v_lshl_add_u64 v[82:83], v[180:181], 2, s[6:7]
	global_atomic_add_f32 v[82:83], v84, off
.LBB0_593:
	s_or_b64 exec, exec, s[20:21]
	v_lshlrev_b32_e32 v84, 16, v135
	v_and_b32_e32 v85, 0xffff0000, v135
	v_lshlrev_b32_e32 v86, 16, v136
	v_and_b32_e32 v87, 0xffff0000, v136
	v_lshlrev_b32_e32 v82, 16, v134
	s_waitcnt lgkmcnt(0)
	v_and_b32_e32 v83, 0xffff0000, v134
	v_lshlrev_b32_e32 v88, 16, v137
	v_and_b32_e32 v89, 0xffff0000, v137
	v_pk_add_f32 v[80:81], v[80:81], v[84:85]
	v_pk_add_f32 v[84:85], v[74:75], v[86:87]
	v_lshlrev_b32_e32 v86, 16, v130
	v_and_b32_e32 v87, 0xffff0000, v130
	v_pk_add_f32 v[78:79], v[78:79], v[82:83]
	v_pk_add_f32 v[82:83], v[76:77], v[88:89]
	v_lshlrev_b32_e32 v88, 16, v131
	v_and_b32_e32 v89, 0xffff0000, v131
	v_lshlrev_b32_e32 v90, 16, v132
	v_and_b32_e32 v91, 0xffff0000, v132
	v_pk_add_f32 v[70:71], v[70:71], v[86:87]
	v_pk_add_f32 v[72:73], v[72:73], v[88:89]
	v_pk_add_f32 v[88:89], v[66:67], v[90:91]
	v_mul_f32_e32 v66, v79, v79
	v_mul_f32_e32 v67, v71, v71
	v_fmac_f32_e32 v66, v78, v78
	v_fmac_f32_e32 v67, v70, v70
	v_fmac_f32_e32 v66, v80, v80
	v_fmac_f32_e32 v67, v72, v72
	v_fmac_f32_e32 v66, v81, v81
	v_fmac_f32_e32 v67, v73, v73
	v_lshlrev_b32_e32 v92, 16, v133
	v_and_b32_e32 v93, 0xffff0000, v133
	v_fmac_f32_e32 v66, v84, v84
	v_fmac_f32_e32 v67, v88, v88
	v_pk_add_f32 v[86:87], v[68:69], v[92:93]
	v_fmac_f32_e32 v66, v85, v85
	v_fmac_f32_e32 v67, v89, v89
	v_fmac_f32_e32 v66, v82, v82
	v_fmac_f32_e32 v67, v86, v86
	v_fmac_f32_e32 v66, v83, v83
	v_fmac_f32_e32 v67, v87, v87
	v_add_f32_e32 v69, v66, v67
	v_cvt_pk_bf16_f32 v75, v80, v81
	ds_bpermute_b32 v80, v195, v69
	v_lshl_add_u64 v[66:67], s[68:69], 0, v[178:179]
	v_cvt_pk_bf16_f32 v74, v78, v79
	v_lshl_add_u64 v[78:79], v[170:171], 1, v[66:67]
	v_cvt_pk_bf16_f32 v76, v84, v85
	s_waitcnt lgkmcnt(0)
	v_add_f32_e32 v66, v69, v80
	ds_bpermute_b32 v67, v114, v66
	v_cvt_pk_bf16_f32 v77, v82, v83
	v_cvt_pk_bf16_f32 v68, v70, v71
	v_cvt_pk_bf16_f32 v69, v72, v73
	v_cvt_pk_bf16_f32 v70, v88, v89
	v_cvt_pk_bf16_f32 v71, v86, v87
	global_store_dwordx4 v[78:79], v[74:77], off nt
	global_store_dwordx4 v[78:79], v[68:71], off offset:256 nt
	s_and_saveexec_b64 s[20:21], s[2:3]
	s_cbranch_execz .LBB0_595
	s_waitcnt lgkmcnt(0)
	v_add_f32_e32 v68, v66, v67
	v_lshl_add_u64 v[66:67], v[176:177], 2, s[6:7]
	global_atomic_add_f32 v[66:67], v68, off
.LBB0_595:
	s_or_b64 exec, exec, s[20:21]
	v_add_u32_e32 v102, 0x80, v174
	v_ashrrev_i32_e32 v103, 31, v102
	v_lshlrev_b64 v[112:113], 11, v[102:103]
	s_waitcnt lgkmcnt(0)
	v_lshl_add_u64 v[66:67], v[172:173], 0, v[112:113]
	global_load_dwordx4 v[104:107], v[66:67], off
	global_load_dwordx4 v[108:111], v[66:67], off offset:256
	v_add_u32_e32 v98, 0x90, v174
	v_add_u32_e32 v94, 0xa0, v174
	v_add_u32_e32 v90, 0xb0, v174
	v_ashrrev_i32_e32 v99, 31, v98
	v_ashrrev_i32_e32 v95, 31, v94
	v_ashrrev_i32_e32 v91, 31, v90
	v_lshlrev_b64 v[100:101], 11, v[98:99]
	v_lshlrev_b64 v[96:97], 11, v[94:95]
	v_lshlrev_b64 v[92:93], 11, v[90:91]
	v_lshl_add_u64 v[66:67], v[172:173], 0, v[100:101]
	v_lshl_add_u64 v[68:69], v[172:173], 0, v[96:97]
	v_lshl_add_u64 v[116:117], v[172:173], 0, v[92:93]
	global_load_dwordx4 v[86:89], v[66:67], off
	global_load_dwordx4 v[82:85], v[66:67], off offset:256
	global_load_dwordx4 v[78:81], v[68:69], off
	global_load_dwordx4 v[74:77], v[68:69], off offset:256
	global_load_dwordx4 v[70:73], v[116:117], off
	s_nop 0
	global_load_dwordx4 v[66:69], v[116:117], off offset:256
	s_waitcnt vmcnt(7)
	v_lshlrev_b32_e32 v116, 16, v104
	v_and_b32_e32 v117, 0xffff0000, v104
	s_waitcnt vmcnt(6)
	v_lshlrev_b32_e32 v120, 16, v108
	v_and_b32_e32 v121, 0xffff0000, v108
	v_lshlrev_b32_e32 v118, 16, v106
	v_and_b32_e32 v119, 0xffff0000, v106
	v_lshlrev_b32_e32 v106, 16, v107
	v_and_b32_e32 v107, 0xffff0000, v107
	v_lshlrev_b32_e32 v108, 16, v109
	v_and_b32_e32 v109, 0xffff0000, v109
	v_lshlrev_b32_e32 v122, 16, v110
	v_and_b32_e32 v123, 0xffff0000, v110
	v_pk_add_f32 v[62:63], v[62:63], v[116:117]
	v_pk_add_f32 v[54:55], v[54:55], v[120:121]
	v_lshlrev_b32_e32 v104, 16, v105
	v_and_b32_e32 v105, 0xffff0000, v105
	v_pk_add_f32 v[60:61], v[60:61], v[106:107]
	v_pk_add_f32 v[56:57], v[56:57], v[108:109]
	v_pk_add_f32 v[106:107], v[50:51], v[122:123]
	v_cvt_pk_bf16_f32 v50, v62, v63
	v_mul_f32_e32 v63, v63, v63
	v_mul_f32_e32 v108, v55, v55
	v_pk_add_f32 v[64:65], v[64:65], v[104:105]
	v_fmac_f32_e32 v63, v62, v62
	v_fmac_f32_e32 v108, v54, v54
	v_fmac_f32_e32 v63, v64, v64
	v_fmac_f32_e32 v108, v56, v56
	v_pk_add_f32 v[58:59], v[58:59], v[118:119]
	v_fmac_f32_e32 v63, v65, v65
	v_fmac_f32_e32 v108, v57, v57
	v_lshlrev_b32_e32 v110, 16, v111
	v_and_b32_e32 v111, 0xffff0000, v111
	v_fmac_f32_e32 v63, v58, v58
	v_fmac_f32_e32 v108, v106, v106
	v_pk_add_f32 v[104:105], v[52:53], v[110:111]
	v_fmac_f32_e32 v63, v59, v59
	v_fmac_f32_e32 v108, v107, v107
	v_fmac_f32_e32 v63, v60, v60
	v_fmac_f32_e32 v108, v104, v104
	v_fmac_f32_e32 v63, v61, v61
	v_fmac_f32_e32 v108, v105, v105
	v_cvt_pk_bf16_f32 v53, v60, v61
	v_add_f32_e32 v60, v63, v108
	ds_bpermute_b32 v61, v195, v60
	v_cvt_pk_bf16_f32 v52, v58, v59
	v_lshl_add_u64 v[58:59], s[68:69], 0, v[112:113]
	v_cvt_pk_bf16_f32 v51, v64, v65
	v_lshl_add_u64 v[58:59], v[170:171], 1, v[58:59]
	global_store_dwordx4 v[58:59], v[50:53], off nt
	s_waitcnt lgkmcnt(0)
	s_nop 0
	v_add_f32_e32 v50, v60, v61
	ds_bpermute_b32 v51, v114, v50
	v_cvt_pk_bf16_f32 v52, v54, v55
	v_cvt_pk_bf16_f32 v53, v56, v57
	v_cvt_pk_bf16_f32 v54, v106, v107
	v_cvt_pk_bf16_f32 v55, v104, v105
	global_store_dwordx4 v[58:59], v[52:55], off offset:256 nt
	s_and_saveexec_b64 s[20:21], s[2:3]
	s_cbranch_execz .LBB0_597
	s_waitcnt lgkmcnt(0)
	v_add_f32_e32 v52, v50, v51
	v_lshl_add_u64 v[50:51], v[102:103], 2, s[6:7]
	global_atomic_add_f32 v[50:51], v52, off
.LBB0_597:
	s_or_b64 exec, exec, s[20:21]
	s_waitcnt vmcnt(7)
	v_lshlrev_b32_e32 v52, 16, v87
	v_and_b32_e32 v53, 0xffff0000, v87
	v_lshlrev_b32_e32 v54, 16, v88
	v_and_b32_e32 v55, 0xffff0000, v88
	v_lshlrev_b32_e32 v50, 16, v86
	s_waitcnt lgkmcnt(0)
	v_and_b32_e32 v51, 0xffff0000, v86
	v_lshlrev_b32_e32 v56, 16, v89
	v_and_b32_e32 v57, 0xffff0000, v89
	v_pk_add_f32 v[48:49], v[48:49], v[52:53]
	v_pk_add_f32 v[52:53], v[42:43], v[54:55]
	s_waitcnt vmcnt(6)
	v_lshlrev_b32_e32 v54, 16, v82
	v_and_b32_e32 v55, 0xffff0000, v82
	v_pk_add_f32 v[46:47], v[46:47], v[50:51]
	v_pk_add_f32 v[50:51], v[44:45], v[56:57]
	v_lshlrev_b32_e32 v56, 16, v83
	v_and_b32_e32 v57, 0xffff0000, v83
	v_lshlrev_b32_e32 v58, 16, v84
	v_and_b32_e32 v59, 0xffff0000, v84
	v_pk_add_f32 v[38:39], v[38:39], v[54:55]
	v_pk_add_f32 v[40:41], v[40:41], v[56:57]
	v_pk_add_f32 v[56:57], v[34:35], v[58:59]
	v_mul_f32_e32 v34, v47, v47
	v_mul_f32_e32 v35, v39, v39
	v_fmac_f32_e32 v34, v46, v46
	v_fmac_f32_e32 v35, v38, v38
	v_fmac_f32_e32 v34, v48, v48
	v_fmac_f32_e32 v35, v40, v40
	v_fmac_f32_e32 v34, v49, v49
	v_fmac_f32_e32 v35, v41, v41
	v_lshlrev_b32_e32 v60, 16, v85
	v_and_b32_e32 v61, 0xffff0000, v85
	v_fmac_f32_e32 v34, v52, v52
	v_fmac_f32_e32 v35, v56, v56
	v_pk_add_f32 v[54:55], v[36:37], v[60:61]
	v_fmac_f32_e32 v34, v53, v53
	v_fmac_f32_e32 v35, v57, v57
	v_fmac_f32_e32 v34, v50, v50
	v_fmac_f32_e32 v35, v54, v54
	v_fmac_f32_e32 v34, v51, v51
	v_fmac_f32_e32 v35, v55, v55
	v_add_f32_e32 v37, v34, v35
	v_cvt_pk_bf16_f32 v43, v48, v49
	ds_bpermute_b32 v48, v195, v37
	v_lshl_add_u64 v[34:35], s[68:69], 0, v[100:101]
	v_cvt_pk_bf16_f32 v42, v46, v47
	v_lshl_add_u64 v[46:47], v[170:171], 1, v[34:35]
	v_cvt_pk_bf16_f32 v44, v52, v53
	s_waitcnt lgkmcnt(0)
	v_add_f32_e32 v34, v37, v48
	ds_bpermute_b32 v35, v114, v34
	v_cvt_pk_bf16_f32 v45, v50, v51
	v_cvt_pk_bf16_f32 v36, v38, v39
	v_cvt_pk_bf16_f32 v37, v40, v41
	v_cvt_pk_bf16_f32 v38, v56, v57
	v_cvt_pk_bf16_f32 v39, v54, v55
	global_store_dwordx4 v[46:47], v[42:45], off nt
	global_store_dwordx4 v[46:47], v[36:39], off offset:256 nt
	s_and_saveexec_b64 s[20:21], s[2:3]
	s_cbranch_execz .LBB0_599
	s_waitcnt lgkmcnt(0)
	v_add_f32_e32 v36, v34, v35
	v_lshl_add_u64 v[34:35], v[98:99], 2, s[6:7]
	global_atomic_add_f32 v[34:35], v36, off
.LBB0_599:
	s_or_b64 exec, exec, s[20:21]
	s_waitcnt vmcnt(7)
	v_lshlrev_b32_e32 v36, 16, v79
	v_and_b32_e32 v37, 0xffff0000, v79
	v_lshlrev_b32_e32 v38, 16, v80
	v_and_b32_e32 v39, 0xffff0000, v80
	v_lshlrev_b32_e32 v34, 16, v78
	s_waitcnt lgkmcnt(0)
	v_and_b32_e32 v35, 0xffff0000, v78
	v_lshlrev_b32_e32 v40, 16, v81
	v_and_b32_e32 v41, 0xffff0000, v81
	v_pk_add_f32 v[32:33], v[32:33], v[36:37]
	v_pk_add_f32 v[36:37], v[26:27], v[38:39]
	s_waitcnt vmcnt(6)
	v_lshlrev_b32_e32 v38, 16, v74
	v_and_b32_e32 v39, 0xffff0000, v74
	v_pk_add_f32 v[30:31], v[30:31], v[34:35]
	v_pk_add_f32 v[34:35], v[28:29], v[40:41]
	v_lshlrev_b32_e32 v40, 16, v75
	v_and_b32_e32 v41, 0xffff0000, v75
	v_lshlrev_b32_e32 v42, 16, v76
	v_and_b32_e32 v43, 0xffff0000, v76
	v_pk_add_f32 v[22:23], v[22:23], v[38:39]
	v_pk_add_f32 v[24:25], v[24:25], v[40:41]
	v_pk_add_f32 v[40:41], v[18:19], v[42:43]
	v_mul_f32_e32 v18, v31, v31
	v_mul_f32_e32 v19, v23, v23
	v_fmac_f32_e32 v18, v30, v30
	v_fmac_f32_e32 v19, v22, v22
	v_fmac_f32_e32 v18, v32, v32
	v_fmac_f32_e32 v19, v24, v24
	v_fmac_f32_e32 v18, v33, v33
	v_fmac_f32_e32 v19, v25, v25
	v_lshlrev_b32_e32 v44, 16, v77
	v_and_b32_e32 v45, 0xffff0000, v77
	v_fmac_f32_e32 v18, v36, v36
	v_fmac_f32_e32 v19, v40, v40
	v_pk_add_f32 v[38:39], v[20:21], v[44:45]
	v_fmac_f32_e32 v18, v37, v37
	v_fmac_f32_e32 v19, v41, v41
	v_fmac_f32_e32 v18, v34, v34
	v_fmac_f32_e32 v19, v38, v38
	v_fmac_f32_e32 v18, v35, v35
	v_fmac_f32_e32 v19, v39, v39
	v_add_f32_e32 v21, v18, v19
	v_cvt_pk_bf16_f32 v27, v32, v33
	ds_bpermute_b32 v32, v195, v21
	v_lshl_add_u64 v[18:19], s[68:69], 0, v[96:97]
	v_cvt_pk_bf16_f32 v26, v30, v31
	v_lshl_add_u64 v[30:31], v[170:171], 1, v[18:19]
	v_cvt_pk_bf16_f32 v28, v36, v37
	s_waitcnt lgkmcnt(0)
	v_add_f32_e32 v18, v21, v32
	ds_bpermute_b32 v19, v114, v18
	v_cvt_pk_bf16_f32 v29, v34, v35
	v_cvt_pk_bf16_f32 v20, v22, v23
	v_cvt_pk_bf16_f32 v21, v24, v25
	v_cvt_pk_bf16_f32 v22, v40, v41
	v_cvt_pk_bf16_f32 v23, v38, v39
	global_store_dwordx4 v[30:31], v[26:29], off nt
	global_store_dwordx4 v[30:31], v[20:23], off offset:256 nt
	s_and_saveexec_b64 s[20:21], s[2:3]
	s_cbranch_execz .LBB0_601
	s_waitcnt lgkmcnt(0)
	v_add_f32_e32 v20, v18, v19
	v_lshl_add_u64 v[18:19], v[94:95], 2, s[6:7]
	global_atomic_add_f32 v[18:19], v20, off
.LBB0_601:
	s_or_b64 exec, exec, s[20:21]
	s_waitcnt vmcnt(7)
	v_lshlrev_b32_e32 v20, 16, v71
	v_and_b32_e32 v21, 0xffff0000, v71
	v_lshlrev_b32_e32 v22, 16, v72
	v_and_b32_e32 v23, 0xffff0000, v72
	v_lshlrev_b32_e32 v18, 16, v70
	s_waitcnt lgkmcnt(0)
	v_and_b32_e32 v19, 0xffff0000, v70
	v_lshlrev_b32_e32 v24, 16, v73
	v_and_b32_e32 v25, 0xffff0000, v73
	v_pk_add_f32 v[16:17], v[16:17], v[20:21]
	v_pk_add_f32 v[20:21], v[10:11], v[22:23]
	s_waitcnt vmcnt(6)
	v_lshlrev_b32_e32 v22, 16, v66
	v_and_b32_e32 v23, 0xffff0000, v66
	v_pk_add_f32 v[14:15], v[14:15], v[18:19]
	v_pk_add_f32 v[18:19], v[12:13], v[24:25]
	v_lshlrev_b32_e32 v24, 16, v67
	v_and_b32_e32 v25, 0xffff0000, v67
	v_lshlrev_b32_e32 v26, 16, v68
	v_and_b32_e32 v27, 0xffff0000, v68
	v_pk_add_f32 v[6:7], v[6:7], v[22:23]
	v_pk_add_f32 v[8:9], v[8:9], v[24:25]
	v_pk_add_f32 v[24:25], v[2:3], v[26:27]
	v_mul_f32_e32 v2, v15, v15
	v_mul_f32_e32 v3, v7, v7
	v_fmac_f32_e32 v2, v14, v14
	v_fmac_f32_e32 v3, v6, v6
	v_fmac_f32_e32 v2, v16, v16
	v_fmac_f32_e32 v3, v8, v8
	v_fmac_f32_e32 v2, v17, v17
	v_fmac_f32_e32 v3, v9, v9
	v_lshlrev_b32_e32 v28, 16, v69
	v_and_b32_e32 v29, 0xffff0000, v69
	v_fmac_f32_e32 v2, v20, v20
	v_fmac_f32_e32 v3, v24, v24
	v_pk_add_f32 v[22:23], v[4:5], v[28:29]
	v_fmac_f32_e32 v2, v21, v21
	v_fmac_f32_e32 v3, v25, v25
	v_fmac_f32_e32 v2, v18, v18
	v_fmac_f32_e32 v3, v22, v22
	v_fmac_f32_e32 v2, v19, v19
	v_fmac_f32_e32 v3, v23, v23
	v_add_f32_e32 v5, v2, v3
	v_cvt_pk_bf16_f32 v11, v16, v17
	ds_bpermute_b32 v16, v195, v5
	v_lshl_add_u64 v[2:3], s[68:69], 0, v[92:93]
	v_cvt_pk_bf16_f32 v10, v14, v15
	v_lshl_add_u64 v[14:15], v[170:171], 1, v[2:3]
	v_cvt_pk_bf16_f32 v12, v20, v21
	s_waitcnt lgkmcnt(0)
	v_add_f32_e32 v2, v5, v16
	ds_bpermute_b32 v3, v114, v2
	v_cvt_pk_bf16_f32 v13, v18, v19
	v_cvt_pk_bf16_f32 v4, v6, v7
	v_cvt_pk_bf16_f32 v5, v8, v9
	v_cvt_pk_bf16_f32 v6, v24, v25
	v_cvt_pk_bf16_f32 v7, v22, v23
	global_store_dwordx4 v[14:15], v[10:13], off nt
	global_store_dwordx4 v[14:15], v[4:7], off offset:256 nt
	s_and_saveexec_b64 s[20:21], s[2:3]
	s_cbranch_execz .LBB0_578
	s_waitcnt lgkmcnt(0)
	v_add_f32_e32 v4, v2, v3
	v_lshl_add_u64 v[2:3], v[90:91], 2, s[6:7]
	global_atomic_add_f32 v[2:3], v4, off
	s_branch .LBB0_578

.Lgemm_epi4:
	s_mov_b32 s56, 0xbfb8aa3b
	v_lshl_add_u32 v146, s43, 10, v154
	ds_read2_b32 v[234:235], v146 offset1:16
	ds_read2_b32 v[236:237], v146 offset0:32 offset1:48
	ds_read2_b32 v[238:239], v146 offset0:128 offset1:144
	ds_read2_b32 v[240:241], v146 offset0:160 offset1:176
	v_lshl_or_b32 v162, s44, 7, v155
	v_ashrrev_i32_e32 v163, 31, v162
	v_lshl_add_u32 v159, s18, 8, v152
	v_lshlrev_b64 v[242:243], 1, v[162:163]
	v_lshl_add_u64 v[242:243], s[4:5], 0, v[242:243]
	s_and_b64 vcc, exec, s[2:3]
	s_mov_b32 s44, s8
	s_mov_b32 s18, s12
	s_mov_b64 s[22:23], s[16:17]
	s_mov_b64 s[20:21], s[14:15]
	s_mov_b32 s43, s42
	s_waitcnt lgkmcnt(0)
	v_mad_i64_i32 v[244:245], s[0:1], v159, s41, v[242:243]
	v_pk_mul_f32 v[126:127], v[126:127], v[234:235] op_sel_hi:[1,0]
	v_pk_mul_f32 v[128:129], v[128:129], v[234:235] op_sel_hi:[1,0]
	v_pk_mul_f32 v[122:123], v[122:123], v[234:235] op_sel_hi:[1,0]
	v_pk_mul_f32 v[124:125], v[124:125], v[234:235] op_sel_hi:[1,0]
	v_pk_mul_f32 v[118:119], v[118:119], v[234:235] op_sel_hi:[1,0]
	v_pk_mul_f32 v[120:121], v[120:121], v[234:235] op_sel_hi:[1,0]
	v_pk_mul_f32 v[114:115], v[114:115], v[234:235] op_sel_hi:[1,0]
	v_pk_mul_f32 v[116:117], v[116:117], v[234:235] op_sel_hi:[1,0]
	v_pk_mul_f32 v[226:227], v[126:127], s[56:57] op_sel_hi:[1,0]
	v_pk_mul_f32 v[228:229], v[128:129], s[56:57] op_sel_hi:[1,0]
	v_pk_mul_f32 v[230:231], v[122:123], s[56:57] op_sel_hi:[1,0]
	v_pk_mul_f32 v[232:233], v[124:125], s[56:57] op_sel_hi:[1,0]
	v_exp_f32_e32 v226, v226
	v_exp_f32_e32 v227, v227
	v_exp_f32_e32 v228, v228
	v_exp_f32_e32 v229, v229
	v_exp_f32_e32 v230, v230
	v_exp_f32_e32 v231, v231
	v_exp_f32_e32 v232, v232
	v_exp_f32_e32 v233, v233
	v_pk_add_f32 v[226:227], v[226:227], 1.0 op_sel_hi:[1,0]
	v_pk_add_f32 v[228:229], v[228:229], 1.0 op_sel_hi:[1,0]
	v_pk_add_f32 v[230:231], v[230:231], 1.0 op_sel_hi:[1,0]
	v_pk_add_f32 v[232:233], v[232:233], 1.0 op_sel_hi:[1,0]
	v_rcp_f32_e32 v226, v226
	v_rcp_f32_e32 v227, v227
	v_rcp_f32_e32 v228, v228
	v_rcp_f32_e32 v229, v229
	v_rcp_f32_e32 v230, v230
	v_rcp_f32_e32 v231, v231
	v_rcp_f32_e32 v232, v232
	v_rcp_f32_e32 v233, v233
	v_pk_mul_f32 v[126:127], v[126:127], v[226:227]
	v_pk_mul_f32 v[128:129], v[128:129], v[228:229]
	v_pk_mul_f32 v[122:123], v[122:123], v[230:231]
	v_pk_mul_f32 v[124:125], v[124:125], v[232:233]
	v_pk_mul_f32 v[118:119], v[126:127], v[118:119]
	v_pk_mul_f32 v[120:121], v[128:129], v[120:121]
	v_pk_mul_f32 v[114:115], v[122:123], v[114:115]
	v_pk_mul_f32 v[116:117], v[124:125], v[116:117]
	v_cvt_pk_bf16_f32 v118, v118, v119
	v_cvt_pk_bf16_f32 v119, v120, v121
	v_cvt_pk_bf16_f32 v120, v114, v115
	v_cvt_pk_bf16_f32 v121, v116, v117
	global_store_dwordx4 v[244:245], v[118:121], off nt
	v_add_u32_e32 v160, 16, v159
	v_mad_i64_i32 v[164:165], s[0:1], v160, s41, v[242:243]
	v_pk_mul_f32 v[110:111], v[110:111], v[234:235] op_sel:[0,1] op_sel_hi:[1,1]
	v_pk_mul_f32 v[112:113], v[112:113], v[234:235] op_sel:[0,1] op_sel_hi:[1,1]
	v_pk_mul_f32 v[106:107], v[106:107], v[234:235] op_sel:[0,1] op_sel_hi:[1,1]
	v_pk_mul_f32 v[108:109], v[108:109], v[234:235] op_sel:[0,1] op_sel_hi:[1,1]
	v_pk_mul_f32 v[102:103], v[102:103], v[234:235] op_sel:[0,1] op_sel_hi:[1,1]
	v_pk_mul_f32 v[104:105], v[104:105], v[234:235] op_sel:[0,1] op_sel_hi:[1,1]
	v_pk_mul_f32 v[98:99], v[98:99], v[234:235] op_sel:[0,1] op_sel_hi:[1,1]
	v_pk_mul_f32 v[100:101], v[100:101], v[234:235] op_sel:[0,1] op_sel_hi:[1,1]
	v_pk_mul_f32 v[226:227], v[110:111], s[56:57] op_sel_hi:[1,0]
	v_pk_mul_f32 v[228:229], v[112:113], s[56:57] op_sel_hi:[1,0]
	v_pk_mul_f32 v[230:231], v[106:107], s[56:57] op_sel_hi:[1,0]
	v_pk_mul_f32 v[232:233], v[108:109], s[56:57] op_sel_hi:[1,0]
	v_exp_f32_e32 v226, v226
	v_exp_f32_e32 v227, v227
	v_exp_f32_e32 v228, v228
	v_exp_f32_e32 v229, v229
	v_exp_f32_e32 v230, v230
	v_exp_f32_e32 v231, v231
	v_exp_f32_e32 v232, v232
	v_exp_f32_e32 v233, v233
	v_pk_add_f32 v[226:227], v[226:227], 1.0 op_sel_hi:[1,0]
	v_pk_add_f32 v[228:229], v[228:229], 1.0 op_sel_hi:[1,0]
	v_pk_add_f32 v[230:231], v[230:231], 1.0 op_sel_hi:[1,0]
	v_pk_add_f32 v[232:233], v[232:233], 1.0 op_sel_hi:[1,0]
	v_rcp_f32_e32 v226, v226
	v_rcp_f32_e32 v227, v227
	v_rcp_f32_e32 v228, v228
	v_rcp_f32_e32 v229, v229
	v_rcp_f32_e32 v230, v230
	v_rcp_f32_e32 v231, v231
	v_rcp_f32_e32 v232, v232
	v_rcp_f32_e32 v233, v233
	v_pk_mul_f32 v[110:111], v[110:111], v[226:227]
	v_pk_mul_f32 v[112:113], v[112:113], v[228:229]
	v_pk_mul_f32 v[106:107], v[106:107], v[230:231]
	v_pk_mul_f32 v[108:109], v[108:109], v[232:233]
	v_pk_mul_f32 v[102:103], v[110:111], v[102:103]
	v_pk_mul_f32 v[104:105], v[112:113], v[104:105]
	v_pk_mul_f32 v[98:99], v[106:107], v[98:99]
	v_pk_mul_f32 v[100:101], v[108:109], v[100:101]
	v_cvt_pk_bf16_f32 v102, v102, v103
	v_cvt_pk_bf16_f32 v103, v104, v105
	v_cvt_pk_bf16_f32 v104, v98, v99
	v_cvt_pk_bf16_f32 v105, v100, v101
	global_store_dwordx4 v[164:165], v[102:105], off nt
	v_add_u32_e32 v160, 32, v159
	v_mad_i64_i32 v[244:245], s[0:1], v160, s41, v[242:243]
	v_pk_mul_f32 v[94:95], v[94:95], v[236:237] op_sel_hi:[1,0]
	v_pk_mul_f32 v[96:97], v[96:97], v[236:237] op_sel_hi:[1,0]
	v_pk_mul_f32 v[90:91], v[90:91], v[236:237] op_sel_hi:[1,0]
	v_pk_mul_f32 v[92:93], v[92:93], v[236:237] op_sel_hi:[1,0]
	v_pk_mul_f32 v[86:87], v[86:87], v[236:237] op_sel_hi:[1,0]
	v_pk_mul_f32 v[88:89], v[88:89], v[236:237] op_sel_hi:[1,0]
	v_pk_mul_f32 v[82:83], v[82:83], v[236:237] op_sel_hi:[1,0]
	v_pk_mul_f32 v[84:85], v[84:85], v[236:237] op_sel_hi:[1,0]
	v_pk_mul_f32 v[226:227], v[94:95], s[56:57] op_sel_hi:[1,0]
	v_pk_mul_f32 v[228:229], v[96:97], s[56:57] op_sel_hi:[1,0]
	v_pk_mul_f32 v[230:231], v[90:91], s[56:57] op_sel_hi:[1,0]
	v_pk_mul_f32 v[232:233], v[92:93], s[56:57] op_sel_hi:[1,0]
	v_exp_f32_e32 v226, v226
	v_exp_f32_e32 v227, v227
	v_exp_f32_e32 v228, v228
	v_exp_f32_e32 v229, v229
	v_exp_f32_e32 v230, v230
	v_exp_f32_e32 v231, v231
	v_exp_f32_e32 v232, v232
	v_exp_f32_e32 v233, v233
	v_pk_add_f32 v[226:227], v[226:227], 1.0 op_sel_hi:[1,0]
	v_pk_add_f32 v[228:229], v[228:229], 1.0 op_sel_hi:[1,0]
	v_pk_add_f32 v[230:231], v[230:231], 1.0 op_sel_hi:[1,0]
	v_pk_add_f32 v[232:233], v[232:233], 1.0 op_sel_hi:[1,0]
	v_rcp_f32_e32 v226, v226
	v_rcp_f32_e32 v227, v227
	v_rcp_f32_e32 v228, v228
	v_rcp_f32_e32 v229, v229
	v_rcp_f32_e32 v230, v230
	v_rcp_f32_e32 v231, v231
	v_rcp_f32_e32 v232, v232
	v_rcp_f32_e32 v233, v233
	v_pk_mul_f32 v[94:95], v[94:95], v[226:227]
	v_pk_mul_f32 v[96:97], v[96:97], v[228:229]
	v_pk_mul_f32 v[90:91], v[90:91], v[230:231]
	v_pk_mul_f32 v[92:93], v[92:93], v[232:233]
	v_pk_mul_f32 v[86:87], v[94:95], v[86:87]
	v_pk_mul_f32 v[88:89], v[96:97], v[88:89]
	v_pk_mul_f32 v[82:83], v[90:91], v[82:83]
	v_pk_mul_f32 v[84:85], v[92:93], v[84:85]
	v_cvt_pk_bf16_f32 v86, v86, v87
	v_cvt_pk_bf16_f32 v87, v88, v89
	v_cvt_pk_bf16_f32 v88, v82, v83
	v_cvt_pk_bf16_f32 v89, v84, v85
	global_store_dwordx4 v[244:245], v[86:89], off nt
	v_add_u32_e32 v160, 48, v159
	v_mad_i64_i32 v[164:165], s[0:1], v160, s41, v[242:243]
	v_pk_mul_f32 v[78:79], v[78:79], v[236:237] op_sel:[0,1] op_sel_hi:[1,1]
	v_pk_mul_f32 v[80:81], v[80:81], v[236:237] op_sel:[0,1] op_sel_hi:[1,1]
	v_pk_mul_f32 v[74:75], v[74:75], v[236:237] op_sel:[0,1] op_sel_hi:[1,1]
	v_pk_mul_f32 v[76:77], v[76:77], v[236:237] op_sel:[0,1] op_sel_hi:[1,1]
	v_pk_mul_f32 v[70:71], v[70:71], v[236:237] op_sel:[0,1] op_sel_hi:[1,1]
	v_pk_mul_f32 v[72:73], v[72:73], v[236:237] op_sel:[0,1] op_sel_hi:[1,1]
	v_pk_mul_f32 v[66:67], v[66:67], v[236:237] op_sel:[0,1] op_sel_hi:[1,1]
	v_pk_mul_f32 v[68:69], v[68:69], v[236:237] op_sel:[0,1] op_sel_hi:[1,1]
	v_pk_mul_f32 v[226:227], v[78:79], s[56:57] op_sel_hi:[1,0]
	v_pk_mul_f32 v[228:229], v[80:81], s[56:57] op_sel_hi:[1,0]
	v_pk_mul_f32 v[230:231], v[74:75], s[56:57] op_sel_hi:[1,0]
	v_pk_mul_f32 v[232:233], v[76:77], s[56:57] op_sel_hi:[1,0]
	v_exp_f32_e32 v226, v226
	v_exp_f32_e32 v227, v227
	v_exp_f32_e32 v228, v228
	v_exp_f32_e32 v229, v229
	v_exp_f32_e32 v230, v230
	v_exp_f32_e32 v231, v231
	v_exp_f32_e32 v232, v232
	v_exp_f32_e32 v233, v233
	v_pk_add_f32 v[226:227], v[226:227], 1.0 op_sel_hi:[1,0]
	v_pk_add_f32 v[228:229], v[228:229], 1.0 op_sel_hi:[1,0]
	v_pk_add_f32 v[230:231], v[230:231], 1.0 op_sel_hi:[1,0]
	v_pk_add_f32 v[232:233], v[232:233], 1.0 op_sel_hi:[1,0]
	v_rcp_f32_e32 v226, v226
	v_rcp_f32_e32 v227, v227
	v_rcp_f32_e32 v228, v228
	v_rcp_f32_e32 v229, v229
	v_rcp_f32_e32 v230, v230
	v_rcp_f32_e32 v231, v231
	v_rcp_f32_e32 v232, v232
	v_rcp_f32_e32 v233, v233
	v_pk_mul_f32 v[78:79], v[78:79], v[226:227]
	v_pk_mul_f32 v[80:81], v[80:81], v[228:229]
	v_pk_mul_f32 v[74:75], v[74:75], v[230:231]
	v_pk_mul_f32 v[76:77], v[76:77], v[232:233]
	v_pk_mul_f32 v[70:71], v[78:79], v[70:71]
	v_pk_mul_f32 v[72:73], v[80:81], v[72:73]
	v_pk_mul_f32 v[66:67], v[74:75], v[66:67]
	v_pk_mul_f32 v[68:69], v[76:77], v[68:69]
	v_cvt_pk_bf16_f32 v70, v70, v71
	v_cvt_pk_bf16_f32 v71, v72, v73
	v_cvt_pk_bf16_f32 v72, v66, v67
	v_cvt_pk_bf16_f32 v73, v68, v69
	global_store_dwordx4 v[164:165], v[70:73], off nt
	v_add_u32_e32 v160, 128, v159
	v_mad_i64_i32 v[244:245], s[0:1], v160, s41, v[242:243]
	v_pk_mul_f32 v[62:63], v[62:63], v[238:239] op_sel_hi:[1,0]
	v_pk_mul_f32 v[64:65], v[64:65], v[238:239] op_sel_hi:[1,0]
	v_pk_mul_f32 v[58:59], v[58:59], v[238:239] op_sel_hi:[1,0]
	v_pk_mul_f32 v[60:61], v[60:61], v[238:239] op_sel_hi:[1,0]
	v_pk_mul_f32 v[54:55], v[54:55], v[238:239] op_sel_hi:[1,0]
	v_pk_mul_f32 v[56:57], v[56:57], v[238:239] op_sel_hi:[1,0]
	v_pk_mul_f32 v[50:51], v[50:51], v[238:239] op_sel_hi:[1,0]
	v_pk_mul_f32 v[52:53], v[52:53], v[238:239] op_sel_hi:[1,0]
	v_pk_mul_f32 v[226:227], v[62:63], s[56:57] op_sel_hi:[1,0]
	v_pk_mul_f32 v[228:229], v[64:65], s[56:57] op_sel_hi:[1,0]
	v_pk_mul_f32 v[230:231], v[58:59], s[56:57] op_sel_hi:[1,0]
	v_pk_mul_f32 v[232:233], v[60:61], s[56:57] op_sel_hi:[1,0]
	v_exp_f32_e32 v226, v226
	v_exp_f32_e32 v227, v227
	v_exp_f32_e32 v228, v228
	v_exp_f32_e32 v229, v229
	v_exp_f32_e32 v230, v230
	v_exp_f32_e32 v231, v231
	v_exp_f32_e32 v232, v232
	v_exp_f32_e32 v233, v233
	v_pk_add_f32 v[226:227], v[226:227], 1.0 op_sel_hi:[1,0]
	v_pk_add_f32 v[228:229], v[228:229], 1.0 op_sel_hi:[1,0]
	v_pk_add_f32 v[230:231], v[230:231], 1.0 op_sel_hi:[1,0]
	v_pk_add_f32 v[232:233], v[232:233], 1.0 op_sel_hi:[1,0]
	v_rcp_f32_e32 v226, v226
	v_rcp_f32_e32 v227, v227
	v_rcp_f32_e32 v228, v228
	v_rcp_f32_e32 v229, v229
	v_rcp_f32_e32 v230, v230
	v_rcp_f32_e32 v231, v231
	v_rcp_f32_e32 v232, v232
	v_rcp_f32_e32 v233, v233
	v_pk_mul_f32 v[62:63], v[62:63], v[226:227]
	v_pk_mul_f32 v[64:65], v[64:65], v[228:229]
	v_pk_mul_f32 v[58:59], v[58:59], v[230:231]
	v_pk_mul_f32 v[60:61], v[60:61], v[232:233]
	v_pk_mul_f32 v[54:55], v[62:63], v[54:55]
	v_pk_mul_f32 v[56:57], v[64:65], v[56:57]
	v_pk_mul_f32 v[50:51], v[58:59], v[50:51]
	v_pk_mul_f32 v[52:53], v[60:61], v[52:53]
	v_cvt_pk_bf16_f32 v54, v54, v55
	v_cvt_pk_bf16_f32 v55, v56, v57
	v_cvt_pk_bf16_f32 v56, v50, v51
	v_cvt_pk_bf16_f32 v57, v52, v53
	global_store_dwordx4 v[244:245], v[54:57], off nt
	v_add_u32_e32 v160, 144, v159
	v_mad_i64_i32 v[164:165], s[0:1], v160, s41, v[242:243]
	v_pk_mul_f32 v[46:47], v[46:47], v[238:239] op_sel:[0,1] op_sel_hi:[1,1]
	v_pk_mul_f32 v[48:49], v[48:49], v[238:239] op_sel:[0,1] op_sel_hi:[1,1]
	v_pk_mul_f32 v[42:43], v[42:43], v[238:239] op_sel:[0,1] op_sel_hi:[1,1]
	v_pk_mul_f32 v[44:45], v[44:45], v[238:239] op_sel:[0,1] op_sel_hi:[1,1]
	v_pk_mul_f32 v[38:39], v[38:39], v[238:239] op_sel:[0,1] op_sel_hi:[1,1]
	v_pk_mul_f32 v[40:41], v[40:41], v[238:239] op_sel:[0,1] op_sel_hi:[1,1]
	v_pk_mul_f32 v[34:35], v[34:35], v[238:239] op_sel:[0,1] op_sel_hi:[1,1]
	v_pk_mul_f32 v[36:37], v[36:37], v[238:239] op_sel:[0,1] op_sel_hi:[1,1]
	v_pk_mul_f32 v[226:227], v[46:47], s[56:57] op_sel_hi:[1,0]
	v_pk_mul_f32 v[228:229], v[48:49], s[56:57] op_sel_hi:[1,0]
	v_pk_mul_f32 v[230:231], v[42:43], s[56:57] op_sel_hi:[1,0]
	v_pk_mul_f32 v[232:233], v[44:45], s[56:57] op_sel_hi:[1,0]
	v_exp_f32_e32 v226, v226
	v_exp_f32_e32 v227, v227
	v_exp_f32_e32 v228, v228
	v_exp_f32_e32 v229, v229
	v_exp_f32_e32 v230, v230
	v_exp_f32_e32 v231, v231
	v_exp_f32_e32 v232, v232
	v_exp_f32_e32 v233, v233
	v_pk_add_f32 v[226:227], v[226:227], 1.0 op_sel_hi:[1,0]
	v_pk_add_f32 v[228:229], v[228:229], 1.0 op_sel_hi:[1,0]
	v_pk_add_f32 v[230:231], v[230:231], 1.0 op_sel_hi:[1,0]
	v_pk_add_f32 v[232:233], v[232:233], 1.0 op_sel_hi:[1,0]
	v_rcp_f32_e32 v226, v226
	v_rcp_f32_e32 v227, v227
	v_rcp_f32_e32 v228, v228
	v_rcp_f32_e32 v229, v229
	v_rcp_f32_e32 v230, v230
	v_rcp_f32_e32 v231, v231
	v_rcp_f32_e32 v232, v232
	v_rcp_f32_e32 v233, v233
	v_pk_mul_f32 v[46:47], v[46:47], v[226:227]
	v_pk_mul_f32 v[48:49], v[48:49], v[228:229]
	v_pk_mul_f32 v[42:43], v[42:43], v[230:231]
	v_pk_mul_f32 v[44:45], v[44:45], v[232:233]
	v_pk_mul_f32 v[38:39], v[46:47], v[38:39]
	v_pk_mul_f32 v[40:41], v[48:49], v[40:41]
	v_pk_mul_f32 v[34:35], v[42:43], v[34:35]
	v_pk_mul_f32 v[36:37], v[44:45], v[36:37]
	v_cvt_pk_bf16_f32 v38, v38, v39
	v_cvt_pk_bf16_f32 v39, v40, v41
	v_cvt_pk_bf16_f32 v40, v34, v35
	v_cvt_pk_bf16_f32 v41, v36, v37
	global_store_dwordx4 v[164:165], v[38:41], off nt
	v_add_u32_e32 v160, 160, v159
	v_mad_i64_i32 v[244:245], s[0:1], v160, s41, v[242:243]
	v_pk_mul_f32 v[30:31], v[30:31], v[240:241] op_sel_hi:[1,0]
	v_pk_mul_f32 v[32:33], v[32:33], v[240:241] op_sel_hi:[1,0]
	v_pk_mul_f32 v[26:27], v[26:27], v[240:241] op_sel_hi:[1,0]
	v_pk_mul_f32 v[28:29], v[28:29], v[240:241] op_sel_hi:[1,0]
	v_pk_mul_f32 v[22:23], v[22:23], v[240:241] op_sel_hi:[1,0]
	v_pk_mul_f32 v[24:25], v[24:25], v[240:241] op_sel_hi:[1,0]
	v_pk_mul_f32 v[18:19], v[18:19], v[240:241] op_sel_hi:[1,0]
	v_pk_mul_f32 v[20:21], v[20:21], v[240:241] op_sel_hi:[1,0]
	v_pk_mul_f32 v[226:227], v[30:31], s[56:57] op_sel_hi:[1,0]
	v_pk_mul_f32 v[228:229], v[32:33], s[56:57] op_sel_hi:[1,0]
	v_pk_mul_f32 v[230:231], v[26:27], s[56:57] op_sel_hi:[1,0]
	v_pk_mul_f32 v[232:233], v[28:29], s[56:57] op_sel_hi:[1,0]
	v_exp_f32_e32 v226, v226
	v_exp_f32_e32 v227, v227
	v_exp_f32_e32 v228, v228
	v_exp_f32_e32 v229, v229
	v_exp_f32_e32 v230, v230
	v_exp_f32_e32 v231, v231
	v_exp_f32_e32 v232, v232
	v_exp_f32_e32 v233, v233
	v_pk_add_f32 v[226:227], v[226:227], 1.0 op_sel_hi:[1,0]
	v_pk_add_f32 v[228:229], v[228:229], 1.0 op_sel_hi:[1,0]
	v_pk_add_f32 v[230:231], v[230:231], 1.0 op_sel_hi:[1,0]
	v_pk_add_f32 v[232:233], v[232:233], 1.0 op_sel_hi:[1,0]
	v_rcp_f32_e32 v226, v226
	v_rcp_f32_e32 v227, v227
	v_rcp_f32_e32 v228, v228
	v_rcp_f32_e32 v229, v229
	v_rcp_f32_e32 v230, v230
	v_rcp_f32_e32 v231, v231
	v_rcp_f32_e32 v232, v232
	v_rcp_f32_e32 v233, v233
	v_pk_mul_f32 v[30:31], v[30:31], v[226:227]
	v_pk_mul_f32 v[32:33], v[32:33], v[228:229]
	v_pk_mul_f32 v[26:27], v[26:27], v[230:231]
	v_pk_mul_f32 v[28:29], v[28:29], v[232:233]
	v_pk_mul_f32 v[22:23], v[30:31], v[22:23]
	v_pk_mul_f32 v[24:25], v[32:33], v[24:25]
	v_pk_mul_f32 v[18:19], v[26:27], v[18:19]
	v_pk_mul_f32 v[20:21], v[28:29], v[20:21]
	v_cvt_pk_bf16_f32 v22, v22, v23
	v_cvt_pk_bf16_f32 v23, v24, v25
	v_cvt_pk_bf16_f32 v24, v18, v19
	v_cvt_pk_bf16_f32 v25, v20, v21
	global_store_dwordx4 v[244:245], v[22:25], off nt
	v_add_u32_e32 v160, 176, v159
	v_mad_i64_i32 v[164:165], s[0:1], v160, s41, v[242:243]
	v_pk_mul_f32 v[14:15], v[14:15], v[240:241] op_sel:[0,1] op_sel_hi:[1,1]
	v_pk_mul_f32 v[16:17], v[16:17], v[240:241] op_sel:[0,1] op_sel_hi:[1,1]
	v_pk_mul_f32 v[10:11], v[10:11], v[240:241] op_sel:[0,1] op_sel_hi:[1,1]
	v_pk_mul_f32 v[12:13], v[12:13], v[240:241] op_sel:[0,1] op_sel_hi:[1,1]
	v_pk_mul_f32 v[6:7], v[6:7], v[240:241] op_sel:[0,1] op_sel_hi:[1,1]
	v_pk_mul_f32 v[8:9], v[8:9], v[240:241] op_sel:[0,1] op_sel_hi:[1,1]
	v_pk_mul_f32 v[2:3], v[2:3], v[240:241] op_sel:[0,1] op_sel_hi:[1,1]
	v_pk_mul_f32 v[4:5], v[4:5], v[240:241] op_sel:[0,1] op_sel_hi:[1,1]
	v_pk_mul_f32 v[226:227], v[14:15], s[56:57] op_sel_hi:[1,0]
	v_pk_mul_f32 v[228:229], v[16:17], s[56:57] op_sel_hi:[1,0]
	v_pk_mul_f32 v[230:231], v[10:11], s[56:57] op_sel_hi:[1,0]
	v_pk_mul_f32 v[232:233], v[12:13], s[56:57] op_sel_hi:[1,0]
	v_exp_f32_e32 v226, v226
	v_exp_f32_e32 v227, v227
	v_exp_f32_e32 v228, v228
	v_exp_f32_e32 v229, v229
	v_exp_f32_e32 v230, v230
	v_exp_f32_e32 v231, v231
	v_exp_f32_e32 v232, v232
	v_exp_f32_e32 v233, v233
	v_pk_add_f32 v[226:227], v[226:227], 1.0 op_sel_hi:[1,0]
	v_pk_add_f32 v[228:229], v[228:229], 1.0 op_sel_hi:[1,0]
	v_pk_add_f32 v[230:231], v[230:231], 1.0 op_sel_hi:[1,0]
	v_pk_add_f32 v[232:233], v[232:233], 1.0 op_sel_hi:[1,0]
	v_rcp_f32_e32 v226, v226
	v_rcp_f32_e32 v227, v227
	v_rcp_f32_e32 v228, v228
	v_rcp_f32_e32 v229, v229
	v_rcp_f32_e32 v230, v230
	v_rcp_f32_e32 v231, v231
	v_rcp_f32_e32 v232, v232
	v_rcp_f32_e32 v233, v233
	v_pk_mul_f32 v[14:15], v[14:15], v[226:227]
	v_pk_mul_f32 v[16:17], v[16:17], v[228:229]
	v_pk_mul_f32 v[10:11], v[10:11], v[230:231]
	v_pk_mul_f32 v[12:13], v[12:13], v[232:233]
	v_pk_mul_f32 v[6:7], v[14:15], v[6:7]
	v_pk_mul_f32 v[8:9], v[16:17], v[8:9]
	v_pk_mul_f32 v[2:3], v[10:11], v[2:3]
	v_pk_mul_f32 v[4:5], v[12:13], v[4:5]
	v_cvt_pk_bf16_f32 v6, v6, v7
	v_cvt_pk_bf16_f32 v7, v8, v9
	v_cvt_pk_bf16_f32 v8, v2, v3
	v_cvt_pk_bf16_f32 v9, v4, v5
	global_store_dwordx4 v[164:165], v[6:9], off nt
	s_cbranch_vccz .LBB0_659
	s_waitcnt vmcnt(0)
	s_cmpk_gt_u32 s26, 0xff
	s_cbranch_scc1 .LBB0_666
	s_barrier

.Lgemm_epi5:
	v_lshl_add_u32 v148, s40, 8, v153
	v_lshl_or_b32 v144, s41, 8, v155
	v_ashrrev_i32_e32 v145, 31, v144
	v_ashrrev_i32_e32 v149, 31, v148
	v_lshl_add_u64 v[146:147], v[144:145], 1, s[14:15]
	v_lshlrev_b64 v[150:151], 11, v[148:149]
	v_or_b32_e32 v180, 16, v148
	v_lshl_add_u64 v[150:151], v[146:147], 0, v[150:151]
	v_ashrrev_i32_e32 v181, 31, v180
	global_load_dwordx4 v[160:163], v[150:151], off
	global_load_dwordx4 v[164:167], v[150:151], off offset:256
	v_lshlrev_b64 v[150:151], 11, v[180:181]
	v_or_b32_e32 v192, 32, v148
	v_lshl_add_u64 v[150:151], v[146:147], 0, v[150:151]
	v_ashrrev_i32_e32 v193, 31, v192
	global_load_dwordx4 v[168:171], v[150:151], off
	global_load_dwordx4 v[172:175], v[150:151], off offset:256
	v_lshlrev_b64 v[150:151], 11, v[192:193]
	v_lshl_add_u64 v[182:183], v[146:147], 0, v[150:151]
	global_load_dwordx4 v[176:179], v[182:183], off
	v_or_b32_e32 v150, 48, v148
	v_ashrrev_i32_e32 v151, 31, v150
	v_lshlrev_b64 v[188:189], 12, v[180:181]
	global_load_dwordx4 v[180:183], v[182:183], off offset:256
	v_lshlrev_b64 v[184:185], 12, v[148:149]
	v_lshlrev_b64 v[186:187], 11, v[150:151]
	v_lshlrev_b64 v[144:145], 2, v[144:145]
	v_lshl_add_u64 v[184:185], s[12:13], 0, v[184:185]
	v_lshl_add_u64 v[190:191], v[146:147], 0, v[186:187]
	v_lshl_add_u64 v[194:195], v[184:185], 0, v[144:145]
	v_lshl_add_u64 v[196:197], s[12:13], 0, v[188:189]
	global_load_dwordx4 v[184:187], v[190:191], off
	s_nop 0
	global_load_dwordx4 v[188:191], v[190:191], off offset:256
	v_lshl_add_u64 v[196:197], v[196:197], 0, v[144:145]
	s_and_b64 vcc, exec, s[0:1]
	s_mov_b32 s41, s38
	s_mov_b32 s40, s39
	s_mov_b64 s[16:17], s[4:5]
	s_mov_b64 s[8:9], s[2:3]
	s_waitcnt vmcnt(0)
	v_lshlrev_b32_e32 v198, 16, v160
	v_and_b32_e32 v199, 0xffff0000, v160
	v_lshlrev_b32_e32 v160, 16, v161
	v_and_b32_e32 v161, 0xffff0000, v161
	v_lshlrev_b32_e32 v200, 16, v162
	v_and_b32_e32 v201, 0xffff0000, v162
	v_lshlrev_b32_e32 v162, 16, v163
	v_and_b32_e32 v163, 0xffff0000, v163
	v_lshlrev_b32_e32 v202, 16, v164
	v_and_b32_e32 v203, 0xffff0000, v164
	v_lshlrev_b32_e32 v164, 16, v165
	v_and_b32_e32 v165, 0xffff0000, v165
	v_lshlrev_b32_e32 v204, 16, v166
	v_and_b32_e32 v205, 0xffff0000, v166
	v_lshlrev_b32_e32 v166, 16, v167
	v_and_b32_e32 v167, 0xffff0000, v167
	v_pk_fma_f32 v[126:127], v[126:127], 0.5, v[160:161] op_sel_hi:[1,0,1]
	v_pk_fma_f32 v[122:123], v[122:123], 0.5, v[162:163] op_sel_hi:[1,0,1]
	v_pk_fma_f32 v[118:119], v[118:119], 0.5, v[164:165] op_sel_hi:[1,0,1]
	v_pk_fma_f32 v[114:115], v[114:115], 0.5, v[166:167] op_sel_hi:[1,0,1]
	v_lshlrev_b32_e32 v160, 16, v168
	v_and_b32_e32 v161, 0xffff0000, v168
	v_lshlrev_b32_e32 v162, 16, v169
	v_and_b32_e32 v163, 0xffff0000, v169
	v_lshlrev_b32_e32 v164, 16, v170
	v_and_b32_e32 v165, 0xffff0000, v170
	v_lshlrev_b32_e32 v166, 16, v171
	v_and_b32_e32 v167, 0xffff0000, v171
	v_lshlrev_b32_e32 v168, 16, v172
	v_and_b32_e32 v169, 0xffff0000, v172
	v_lshlrev_b32_e32 v170, 16, v173
	v_and_b32_e32 v171, 0xffff0000, v173
	v_lshlrev_b32_e32 v172, 16, v174
	v_and_b32_e32 v173, 0xffff0000, v174
	v_pk_fma_f32 v[124:125], v[124:125], 0.5, v[198:199] op_sel_hi:[1,0,1]
	v_lshlrev_b32_e32 v174, 16, v175
	v_and_b32_e32 v175, 0xffff0000, v175
	v_pk_fma_f32 v[110:111], v[110:111], 0.5, v[162:163] op_sel_hi:[1,0,1]
	v_pk_fma_f32 v[108:109], v[108:109], 0.5, v[160:161] op_sel_hi:[1,0,1]
	v_pk_fma_f32 v[96:97], v[96:97], 0.5, v[172:173] op_sel_hi:[1,0,1]
	v_pk_fma_f32 v[120:121], v[120:121], 0.5, v[200:201] op_sel_hi:[1,0,1]
	v_pk_fma_f32 v[116:117], v[116:117], 0.5, v[202:203] op_sel_hi:[1,0,1]
	v_pk_fma_f32 v[112:113], v[112:113], 0.5, v[204:205] op_sel_hi:[1,0,1]
	global_store_dwordx4 v[194:195], v[124:127], off nt
	global_store_dwordx4 v[194:195], v[120:123], off offset:16 nt
	global_store_dwordx4 v[194:195], v[116:119], off offset:512 nt
	global_store_dwordx4 v[194:195], v[112:115], off offset:528 nt
	v_pk_fma_f32 v[106:107], v[106:107], 0.5, v[166:167] op_sel_hi:[1,0,1]
	v_pk_fma_f32 v[104:105], v[104:105], 0.5, v[164:165] op_sel_hi:[1,0,1]
	v_pk_fma_f32 v[102:103], v[102:103], 0.5, v[170:171] op_sel_hi:[1,0,1]
	v_pk_fma_f32 v[100:101], v[100:101], 0.5, v[168:169] op_sel_hi:[1,0,1]
	v_pk_fma_f32 v[98:99], v[98:99], 0.5, v[174:175] op_sel_hi:[1,0,1]
	global_store_dwordx4 v[196:197], v[108:111], off nt
	global_store_dwordx4 v[196:197], v[104:107], off offset:16 nt
	global_store_dwordx4 v[196:197], v[100:103], off offset:512 nt
	global_store_dwordx4 v[196:197], v[96:99], off offset:528 nt
	s_nop 0
	v_lshlrev_b32_e32 v100, 16, v178
	v_lshlrev_b32_e32 v96, 16, v176
	v_and_b32_e32 v97, 0xffff0000, v176
	v_pk_fma_f32 v[92:93], v[92:93], 0.5, v[96:97] op_sel_hi:[1,0,1]
	v_lshlrev_b64 v[96:97], 12, v[192:193]
	v_lshlrev_b32_e32 v98, 16, v177
	v_and_b32_e32 v99, 0xffff0000, v177
	v_and_b32_e32 v101, 0xffff0000, v178
	v_lshlrev_b32_e32 v102, 16, v179
	v_and_b32_e32 v103, 0xffff0000, v179
	v_lshl_add_u64 v[96:97], s[12:13], 0, v[96:97]
	v_pk_fma_f32 v[94:95], v[94:95], 0.5, v[98:99] op_sel_hi:[1,0,1]
	v_pk_fma_f32 v[90:91], v[90:91], 0.5, v[102:103] op_sel_hi:[1,0,1]
	v_pk_fma_f32 v[88:89], v[88:89], 0.5, v[100:101] op_sel_hi:[1,0,1]
	v_lshl_add_u64 v[96:97], v[96:97], 0, v[144:145]
	global_store_dwordx4 v[96:97], v[92:95], off nt
	global_store_dwordx4 v[96:97], v[88:91], off offset:16 nt
	v_add_u32_e32 v98, 0x90, v148
	v_lshlrev_b32_e32 v92, 16, v182
	v_lshlrev_b32_e32 v88, 16, v180
	v_and_b32_e32 v89, 0xffff0000, v180
	v_lshlrev_b32_e32 v90, 16, v181
	v_and_b32_e32 v91, 0xffff0000, v181
	v_and_b32_e32 v93, 0xffff0000, v182
	v_lshlrev_b32_e32 v94, 16, v183
	v_and_b32_e32 v95, 0xffff0000, v183
	v_pk_fma_f32 v[86:87], v[86:87], 0.5, v[90:91] op_sel_hi:[1,0,1]
	v_pk_fma_f32 v[84:85], v[84:85], 0.5, v[88:89] op_sel_hi:[1,0,1]
	v_pk_fma_f32 v[76:77], v[76:77], 0.5, v[92:93] op_sel_hi:[1,0,1]
	v_pk_fma_f32 v[78:79], v[78:79], 0.5, v[94:95] op_sel_hi:[1,0,1]
	global_store_dwordx4 v[96:97], v[84:87], off offset:512 nt
	global_store_dwordx4 v[96:97], v[76:79], off offset:528 nt
	v_add_u32_e32 v96, 0x80, v148
	v_lshlrev_b32_e32 v84, 16, v186
	v_lshlrev_b32_e32 v76, 16, v184
	v_and_b32_e32 v77, 0xffff0000, v184
	v_pk_fma_f32 v[76:77], v[80:81], 0.5, v[76:77] op_sel_hi:[1,0,1]
	v_lshlrev_b64 v[80:81], 12, v[150:151]
	v_lshlrev_b32_e32 v78, 16, v185
	v_and_b32_e32 v79, 0xffff0000, v185
	v_and_b32_e32 v85, 0xffff0000, v186
	v_lshlrev_b32_e32 v86, 16, v187
	v_and_b32_e32 v87, 0xffff0000, v187
	v_lshl_add_u64 v[80:81], s[12:13], 0, v[80:81]
	v_pk_fma_f32 v[78:79], v[82:83], 0.5, v[78:79] op_sel_hi:[1,0,1]
	v_pk_fma_f32 v[74:75], v[74:75], 0.5, v[86:87] op_sel_hi:[1,0,1]
	v_pk_fma_f32 v[72:73], v[72:73], 0.5, v[84:85] op_sel_hi:[1,0,1]
	v_lshl_add_u64 v[80:81], v[80:81], 0, v[144:145]
	global_store_dwordx4 v[80:81], v[76:79], off nt
	global_store_dwordx4 v[80:81], v[72:75], off offset:16 nt
	v_ashrrev_i32_e32 v97, 31, v96
	v_lshlrev_b32_e32 v76, 16, v190
	v_lshlrev_b32_e32 v72, 16, v188
	v_and_b32_e32 v73, 0xffff0000, v188
	v_lshlrev_b32_e32 v74, 16, v189
	v_and_b32_e32 v75, 0xffff0000, v189
	v_and_b32_e32 v77, 0xffff0000, v190
	v_lshlrev_b32_e32 v78, 16, v191
	v_and_b32_e32 v79, 0xffff0000, v191
	v_pk_fma_f32 v[70:71], v[70:71], 0.5, v[74:75] op_sel_hi:[1,0,1]
	v_pk_fma_f32 v[68:69], v[68:69], 0.5, v[72:73] op_sel_hi:[1,0,1]
	v_pk_fma_f32 v[64:65], v[64:65], 0.5, v[76:77] op_sel_hi:[1,0,1]
	v_pk_fma_f32 v[66:67], v[66:67], 0.5, v[78:79] op_sel_hi:[1,0,1]
	global_store_dwordx4 v[80:81], v[68:71], off offset:512 nt
	global_store_dwordx4 v[80:81], v[64:67], off offset:528 nt
	v_ashrrev_i32_e32 v99, 31, v98
	v_add_u32_e32 v100, 0xa0, v148
	v_lshlrev_b64 v[64:65], 11, v[96:97]
	v_lshl_add_u64 v[64:65], v[146:147], 0, v[64:65]
	global_load_dwordx4 v[68:71], v[64:65], off
	global_load_dwordx4 v[72:75], v[64:65], off offset:256
	v_lshlrev_b64 v[64:65], 11, v[98:99]
	v_lshl_add_u64 v[64:65], v[146:147], 0, v[64:65]
	global_load_dwordx4 v[76:79], v[64:65], off
	global_load_dwordx4 v[80:83], v[64:65], off offset:256
	v_ashrrev_i32_e32 v101, 31, v100
	v_lshlrev_b64 v[64:65], 11, v[100:101]
	v_lshl_add_u64 v[64:65], v[146:147], 0, v[64:65]
	global_load_dwordx4 v[84:87], v[64:65], off
	global_load_dwordx4 v[88:91], v[64:65], off offset:256
	v_add_u32_e32 v102, 0xb0, v148
	v_ashrrev_i32_e32 v103, 31, v102
	v_lshlrev_b64 v[64:65], 11, v[102:103]
	v_lshl_add_u64 v[64:65], v[146:147], 0, v[64:65]
	global_load_dwordx4 v[92:95], v[64:65], off
	s_nop 0
	global_load_dwordx4 v[64:67], v[64:65], off offset:256
	s_waitcnt vmcnt(0)
	v_lshlrev_b32_e32 v104, 16, v68
	v_and_b32_e32 v105, 0xffff0000, v68
	v_lshlrev_b32_e32 v68, 16, v69
	v_and_b32_e32 v69, 0xffff0000, v69
	v_pk_fma_f32 v[62:63], v[62:63], 0.5, v[68:69] op_sel_hi:[1,0,1]
	v_lshlrev_b64 v[68:69], 12, v[96:97]
	v_lshlrev_b32_e32 v106, 16, v70
	v_and_b32_e32 v107, 0xffff0000, v70
	v_lshlrev_b32_e32 v70, 16, v71
	v_and_b32_e32 v71, 0xffff0000, v71
	v_lshl_add_u64 v[68:69], s[12:13], 0, v[68:69]
	v_pk_fma_f32 v[60:61], v[60:61], 0.5, v[104:105] op_sel_hi:[1,0,1]
	v_pk_fma_f32 v[58:59], v[58:59], 0.5, v[70:71] op_sel_hi:[1,0,1]
	v_pk_fma_f32 v[56:57], v[56:57], 0.5, v[106:107] op_sel_hi:[1,0,1]
	v_lshl_add_u64 v[68:69], v[68:69], 0, v[144:145]
	global_store_dwordx4 v[68:69], v[60:63], off nt
	global_store_dwordx4 v[68:69], v[56:59], off offset:16 nt
	s_nop 0
	v_lshlrev_b32_e32 v60, 16, v74
	v_lshlrev_b32_e32 v56, 16, v72
	v_and_b32_e32 v57, 0xffff0000, v72
	v_lshlrev_b32_e32 v58, 16, v73
	v_and_b32_e32 v59, 0xffff0000, v73
	v_and_b32_e32 v61, 0xffff0000, v74
	v_lshlrev_b32_e32 v62, 16, v75
	v_and_b32_e32 v63, 0xffff0000, v75
	v_pk_fma_f32 v[54:55], v[54:55], 0.5, v[58:59] op_sel_hi:[1,0,1]
	v_pk_fma_f32 v[52:53], v[52:53], 0.5, v[56:57] op_sel_hi:[1,0,1]
	v_pk_fma_f32 v[44:45], v[44:45], 0.5, v[60:61] op_sel_hi:[1,0,1]
	v_pk_fma_f32 v[46:47], v[46:47], 0.5, v[62:63] op_sel_hi:[1,0,1]
	global_store_dwordx4 v[68:69], v[52:55], off offset:512 nt
	global_store_dwordx4 v[68:69], v[44:47], off offset:528 nt
	s_nop 0
	v_lshlrev_b32_e32 v52, 16, v78
	v_lshlrev_b32_e32 v44, 16, v76
	v_and_b32_e32 v45, 0xffff0000, v76
	v_pk_fma_f32 v[44:45], v[48:49], 0.5, v[44:45] op_sel_hi:[1,0,1]
	v_lshlrev_b64 v[48:49], 12, v[98:99]
	v_lshlrev_b32_e32 v46, 16, v77
	v_and_b32_e32 v47, 0xffff0000, v77
	v_and_b32_e32 v53, 0xffff0000, v78
	v_lshlrev_b32_e32 v54, 16, v79
	v_and_b32_e32 v55, 0xffff0000, v79
	v_lshl_add_u64 v[48:49], s[12:13], 0, v[48:49]
	v_pk_fma_f32 v[46:47], v[50:51], 0.5, v[46:47] op_sel_hi:[1,0,1]
	v_pk_fma_f32 v[42:43], v[42:43], 0.5, v[54:55] op_sel_hi:[1,0,1]
	v_pk_fma_f32 v[40:41], v[40:41], 0.5, v[52:53] op_sel_hi:[1,0,1]
	v_lshl_add_u64 v[48:49], v[48:49], 0, v[144:145]
	global_store_dwordx4 v[48:49], v[44:47], off nt
	global_store_dwordx4 v[48:49], v[40:43], off offset:16 nt
	s_nop 0
	v_lshlrev_b32_e32 v44, 16, v82
	v_lshlrev_b32_e32 v40, 16, v80
	v_and_b32_e32 v41, 0xffff0000, v80
	v_lshlrev_b32_e32 v42, 16, v81
	v_and_b32_e32 v43, 0xffff0000, v81
	v_and_b32_e32 v45, 0xffff0000, v82
	v_lshlrev_b32_e32 v46, 16, v83
	v_and_b32_e32 v47, 0xffff0000, v83
	v_pk_fma_f32 v[38:39], v[38:39], 0.5, v[42:43] op_sel_hi:[1,0,1]
	v_pk_fma_f32 v[36:37], v[36:37], 0.5, v[40:41] op_sel_hi:[1,0,1]
	v_pk_fma_f32 v[28:29], v[28:29], 0.5, v[44:45] op_sel_hi:[1,0,1]
	v_pk_fma_f32 v[30:31], v[30:31], 0.5, v[46:47] op_sel_hi:[1,0,1]
	global_store_dwordx4 v[48:49], v[36:39], off offset:512 nt
	global_store_dwordx4 v[48:49], v[28:31], off offset:528 nt
	s_nop 0
	v_lshlrev_b32_e32 v36, 16, v86
	v_lshlrev_b32_e32 v28, 16, v84
	v_and_b32_e32 v29, 0xffff0000, v84
	v_pk_fma_f32 v[28:29], v[32:33], 0.5, v[28:29] op_sel_hi:[1,0,1]
	v_lshlrev_b64 v[32:33], 12, v[100:101]
	v_lshlrev_b32_e32 v30, 16, v85
	v_and_b32_e32 v31, 0xffff0000, v85
	v_and_b32_e32 v37, 0xffff0000, v86
	v_lshlrev_b32_e32 v38, 16, v87
	v_and_b32_e32 v39, 0xffff0000, v87
	v_lshl_add_u64 v[32:33], s[12:13], 0, v[32:33]
	v_pk_fma_f32 v[30:31], v[34:35], 0.5, v[30:31] op_sel_hi:[1,0,1]
	v_pk_fma_f32 v[26:27], v[26:27], 0.5, v[38:39] op_sel_hi:[1,0,1]
	v_pk_fma_f32 v[24:25], v[24:25], 0.5, v[36:37] op_sel_hi:[1,0,1]
	v_lshl_add_u64 v[32:33], v[32:33], 0, v[144:145]
	global_store_dwordx4 v[32:33], v[28:31], off nt
	global_store_dwordx4 v[32:33], v[24:27], off offset:16 nt
	s_nop 0
	v_lshlrev_b32_e32 v28, 16, v90
	v_lshlrev_b32_e32 v24, 16, v88
	v_and_b32_e32 v25, 0xffff0000, v88
	v_lshlrev_b32_e32 v26, 16, v89
	v_and_b32_e32 v27, 0xffff0000, v89
	v_and_b32_e32 v29, 0xffff0000, v90
	v_lshlrev_b32_e32 v30, 16, v91
	v_and_b32_e32 v31, 0xffff0000, v91
	v_pk_fma_f32 v[22:23], v[22:23], 0.5, v[26:27] op_sel_hi:[1,0,1]
	v_pk_fma_f32 v[20:21], v[20:21], 0.5, v[24:25] op_sel_hi:[1,0,1]
	v_pk_fma_f32 v[12:13], v[12:13], 0.5, v[28:29] op_sel_hi:[1,0,1]
	v_pk_fma_f32 v[14:15], v[14:15], 0.5, v[30:31] op_sel_hi:[1,0,1]
	global_store_dwordx4 v[32:33], v[20:23], off offset:512 nt
	global_store_dwordx4 v[32:33], v[12:15], off offset:528 nt
	s_nop 0
	v_lshlrev_b32_e32 v20, 16, v94
	v_lshlrev_b32_e32 v12, 16, v92
	v_and_b32_e32 v13, 0xffff0000, v92
	v_pk_fma_f32 v[12:13], v[16:17], 0.5, v[12:13] op_sel_hi:[1,0,1]
	v_lshlrev_b64 v[16:17], 12, v[102:103]
	v_lshlrev_b32_e32 v14, 16, v93
	v_and_b32_e32 v15, 0xffff0000, v93
	v_and_b32_e32 v21, 0xffff0000, v94
	v_lshlrev_b32_e32 v22, 16, v95
	v_and_b32_e32 v23, 0xffff0000, v95
	v_lshl_add_u64 v[16:17], s[12:13], 0, v[16:17]
	v_pk_fma_f32 v[14:15], v[18:19], 0.5, v[14:15] op_sel_hi:[1,0,1]
	v_pk_fma_f32 v[10:11], v[10:11], 0.5, v[22:23] op_sel_hi:[1,0,1]
	v_pk_fma_f32 v[8:9], v[8:9], 0.5, v[20:21] op_sel_hi:[1,0,1]
	v_lshl_add_u64 v[16:17], v[16:17], 0, v[144:145]
	global_store_dwordx4 v[16:17], v[12:15], off nt
	global_store_dwordx4 v[16:17], v[8:11], off offset:16 nt
	s_nop 0
	v_lshlrev_b32_e32 v12, 16, v66
	v_lshlrev_b32_e32 v8, 16, v64
	v_and_b32_e32 v9, 0xffff0000, v64
	v_lshlrev_b32_e32 v10, 16, v65
	v_and_b32_e32 v11, 0xffff0000, v65
	v_and_b32_e32 v13, 0xffff0000, v66
	v_lshlrev_b32_e32 v14, 16, v67
	v_and_b32_e32 v15, 0xffff0000, v67
	v_pk_fma_f32 v[6:7], v[6:7], 0.5, v[10:11] op_sel_hi:[1,0,1]
	v_pk_fma_f32 v[4:5], v[4:5], 0.5, v[8:9] op_sel_hi:[1,0,1]
	v_pk_fma_f32 v[2:3], v[2:3], 0.5, v[14:15] op_sel_hi:[1,0,1]
	v_pk_fma_f32 v[0:1], v[0:1], 0.5, v[12:13] op_sel_hi:[1,0,1]
	global_store_dwordx4 v[16:17], v[4:7], off offset:512 nt
	global_store_dwordx4 v[16:17], v[0:3], off offset:528 nt
	s_cbranch_vccz .LBB0_696
	s_waitcnt vmcnt(0)
	s_cmpk_gt_u32 s20, 0xff
	s_cbranch_scc1 .LBB0_711
	s_barrier
